# nt hint on the once-read f32 weight loads of the bf16 conversion blocks (480 loads), on v21
# speedup vs baseline: 1.0039x; 1.0039x over previous
; __device__ __forceinline__ void conv_addr(const ConvJob& j, int wi, int lane, const float*& src, int& stride, bf16_t*& dst, const float*& kg) {
;     ...
;     else { const int nb = wi / 352, k0 = (wi - nb * 352) * 8;
;         src = j.s0 + (size_t)k0 * D + nb * 64 + lane; stride = D; dst = j.dst + (size_t)(nb * 64 + lane) * FF + k0; kg = nullptr; }
; template <int NMAX>
; __device__ __forceinline__ void conv_block(const ConvJob& j, int total, int gw, int NW, int lane) {
;     if (j.kind == 0) return;
;     float v[NMAX][8]; bf16_t* d[NMAX]; const float* kg[NMAX];
; #pragma unroll
;     for (int q = 0; q < NMAX; ++q) { const int wi = gw + q * NW; const float* src; int st;
;         conv_addr(j, wi < total ? wi : gw, lane, src, st, d[q], kg[q]); conv_load(src, st, v[q]); }
.LBB0_216:
	s_cmp_lt_i32 s74, 2
	s_cselect_b64 s[0:1], -1, 0
	s_cmp_gt_i32 s75, 1
	s_cselect_b64 s[2:3], -1, 0
	s_and_b64 s[0:1], s[0:1], s[2:3]
	s_andn2_b64 vcc, exec, s[0:1]
	s_cbranch_vccnz .LBB0_331
	s_mov_b64 s[2:3], s[72:73]
	s_load_dwordx2 s[0:1], s[2:3], 0x30
	s_load_dwordx2 s[10:11], s[2:3], 0xa0
	s_add_i32 s2, 0, 0x2080c
	v_mov_b32_e32 v8, v220
	v_mov_b32_e32 v0, s2
	ds_read_b32 v0, v0
	v_ashrrev_i32_e32 v1, 6, v8
	s_waitcnt lgkmcnt(0)
	s_lshl_b32 s2, s96, 3
	v_and_b32_e32 v146, 63, v8
	v_lshlrev_b32_e32 v128, 2, v146
	v_readfirstlane_b32 s33, v0
	v_lshl_add_u32 v147, v0, 3, v1
	v_and_b32_e32 v0, 1, v0
	v_cmp_eq_u32_e64 s[4:5], 0, v0
	v_add_u32_e32 v149, s2, v147
	s_and_b64 vcc, exec, s[4:5]
	v_add_u32_e32 v148, s2, v149
	s_cbranch_vccnz .LBB0_223
	s_movk_i32 s14, 0x1600
	v_cmp_gt_i32_e64 s[6:7], s14, v149
	s_mov_b32 s15, 0x2e8ba2e9
	v_cmp_gt_i32_e64 s[8:9], s14, v148
	v_cndmask_b32_e64 v0, v147, v149, s[6:7]
	v_mul_hi_i32 v1, v0, s15
	v_lshrrev_b32_e32 v2, 31, v1
	v_ashrrev_i32_e32 v1, 6, v1
	v_add_u32_e32 v6, v1, v2
	v_mul_i32_i24_e32 v1, 0xfffffea0, v6
	v_add_lshl_u32 v0, v1, v0, 3
	v_ashrrev_i32_e32 v1, 31, v0
	v_lshlrev_b64 v[2:3], 12, v[0:1]
	v_lshl_add_u64 v[4:5], s[0:1], 0, v[2:3]
	v_lshlrev_b32_e32 v2, 6, v6
	v_ashrrev_i32_e32 v3, 31, v2
	v_mov_b32_e32 v129, 0
	v_lshl_add_u64 v[4:5], v[2:3], 2, v[4:5]
	v_cndmask_b32_e64 v3, v147, v148, s[8:9]
	v_lshl_add_u64 v[24:25], v[4:5], 0, v[128:129]
	v_mul_hi_i32 v4, v3, s15
	v_lshrrev_b32_e32 v5, 31, v4
	v_ashrrev_i32_e32 v4, 6, v4
	s_movk_i32 s16, 0x2000
	v_add_u32_e32 v9, v4, v5
	v_add_co_u32_e32 v26, vcc, s16, v24
	v_mul_i32_i24_e32 v4, 0xfffffea0, v9
	s_nop 0
	v_addc_co_u32_e32 v27, vcc, 0, v25, vcc
	s_movk_i32 s17, 0x4000
	v_add_lshl_u32 v4, v4, v3, 3
	v_add_co_u32_e32 v16, vcc, s17, v24
	v_ashrrev_i32_e32 v5, 31, v4
	s_nop 0
	v_addc_co_u32_e32 v17, vcc, 0, v25, vcc
	s_movk_i32 s18, 0x6000
	v_lshlrev_b64 v[6:7], 12, v[4:5]
	v_add_co_u32_e32 v18, vcc, s18, v24
	v_lshl_add_u64 v[10:11], s[0:1], 0, v[6:7]
	v_lshlrev_b32_e32 v6, 6, v9
	v_addc_co_u32_e32 v19, vcc, 0, v25, vcc
	s_movk_i32 s3, 0x7000
	v_ashrrev_i32_e32 v7, 31, v6
	v_add_co_u32_e32 v28, vcc, s3, v24
	v_lshl_add_u64 v[10:11], v[6:7], 2, v[10:11]
	s_nop 0
	v_addc_co_u32_e32 v29, vcc, 0, v25, vcc
	v_lshl_add_u64 v[30:31], v[10:11], 0, v[128:129]
	v_add_co_u32_e32 v20, vcc, s16, v30
	s_movk_i32 s2, 0x5000
	s_nop 0
	v_addc_co_u32_e32 v21, vcc, 0, v31, vcc
	v_add_co_u32_e32 v22, vcc, s17, v30
	s_nop 1
	v_addc_co_u32_e32 v23, vcc, 0, v31, vcc
	v_add_co_u32_e32 v32, vcc, s2, v30
	global_load_dword v15, v[16:17], off offset:-4096 nt
	global_load_dword v12, v[16:17], off nt
	global_load_dword v13, v[18:19], off offset:-4096 nt
	global_load_dword v11, v[18:19], off nt
	global_load_dword v9, v[20:21], off offset:-4096 nt
	global_load_dword v3, v[20:21], off nt
	global_load_dword v10, v[22:23], off offset:-4096 nt
	global_load_dword v7, v[22:23], off nt
	v_addc_co_u32_e32 v33, vcc, 0, v31, vcc
	v_add_co_u32_e32 v34, vcc, 0x6000, v30
	s_add_u32 s2, s10, 0xfb00000
	s_nop 0
	v_addc_co_u32_e32 v35, vcc, 0, v31, vcc
	v_add_co_u32_e32 v36, vcc, 0x7000, v30
	s_addc_u32 s3, s11, 0
	s_nop 0
	v_addc_co_u32_e32 v37, vcc, 0, v31, vcc
	global_load_dword v21, v[24:25], off nt
	global_load_dword v22, v[26:27], off offset:-4096 nt
	global_load_dword v20, v[26:27], off nt
	global_load_dword v19, v[28:29], off nt
	global_load_dword v18, v[30:31], off nt
	global_load_dword v16, v[32:33], off nt
	global_load_dword v14, v[34:35], off nt
	global_load_dword v17, v[36:37], off nt
	v_cmp_gt_i32_e32 vcc, s14, v147
	s_and_saveexec_b64 s[12:13], vcc
	s_cbranch_execnz .LBB0_253
	s_or_b64 exec, exec, s[12:13]
	s_and_saveexec_b64 s[12:13], s[6:7]
	s_cbranch_execnz .LBB0_254

; __device__ __forceinline__ void conv_addr(const ConvJob& j, int wi, int lane, const float*& src, int& stride, bf16_t*& dst, const float*& kg) {
;     ...
;     else { const int nb = wi / 352, k0 = (wi - nb * 352) * 8;
;         src = j.s0 + (size_t)k0 * D + nb * 64 + lane; stride = D; dst = j.dst + (size_t)(nb * 64 + lane) * FF + k0; kg = nullptr; }
; template <int NMAX>
; __device__ __forceinline__ void conv_block(const ConvJob& j, int total, int gw, int NW, int lane) {
;     if (j.kind == 0) return;
;     float v[NMAX][8]; bf16_t* d[NMAX]; const float* kg[NMAX];
; #pragma unroll
;     for (int q = 0; q < NMAX; ++q) { const int wi = gw + q * NW; const float* src; int st;
;         conv_addr(j, wi < total ? wi : gw, lane, src, st, d[q], kg[q]); conv_load(src, st, v[q]); }
.LBB0_237:
	s_movk_i32 s12, 0x1600
	v_cmp_gt_i32_e64 s[4:5], s12, v149
	s_mov_b32 s13, 0x2e8ba2e9
	v_cmp_gt_i32_e64 s[6:7], s12, v148
	v_cndmask_b32_e64 v0, v147, v149, s[4:5]
	v_mul_hi_i32 v1, v0, s13
	v_lshrrev_b32_e32 v2, 31, v1
	v_ashrrev_i32_e32 v1, 6, v1
	v_add_u32_e32 v6, v1, v2
	v_mul_i32_i24_e32 v1, 0xfffffea0, v6
	v_add_lshl_u32 v0, v1, v0, 3
	v_ashrrev_i32_e32 v1, 31, v0
	v_lshlrev_b64 v[2:3], 12, v[0:1]
	v_lshl_add_u64 v[4:5], s[0:1], 0, v[2:3]
	v_lshlrev_b32_e32 v2, 6, v6
	v_ashrrev_i32_e32 v3, 31, v2
	v_mov_b32_e32 v129, 0
	v_lshl_add_u64 v[4:5], v[2:3], 2, v[4:5]
	v_cndmask_b32_e64 v3, v147, v148, s[6:7]
	v_lshl_add_u64 v[22:23], v[4:5], 0, v[128:129]
	v_mul_hi_i32 v4, v3, s13
	v_lshrrev_b32_e32 v5, 31, v4
	v_ashrrev_i32_e32 v4, 6, v4
	s_movk_i32 s14, 0x2000
	v_add_u32_e32 v10, v4, v5
	v_add_co_u32_e32 v24, vcc, s14, v22
	v_mul_i32_i24_e32 v4, 0xfffffea0, v10
	s_nop 0
	v_addc_co_u32_e32 v25, vcc, 0, v23, vcc
	s_movk_i32 s15, 0x4000
	v_add_lshl_u32 v4, v4, v3, 3
	v_add_co_u32_e32 v16, vcc, s15, v22
	v_ashrrev_i32_e32 v5, 31, v4
	s_nop 0
	v_addc_co_u32_e32 v17, vcc, 0, v23, vcc
	s_movk_i32 s16, 0x6000
	v_lshlrev_b64 v[6:7], 12, v[4:5]
	v_add_co_u32_e32 v18, vcc, s16, v22
	v_lshl_add_u64 v[8:9], s[0:1], 0, v[6:7]
	v_lshlrev_b32_e32 v6, 6, v10
	v_addc_co_u32_e32 v19, vcc, 0, v23, vcc
	s_movk_i32 s3, 0x7000
	v_ashrrev_i32_e32 v7, 31, v6
	v_add_co_u32_e32 v26, vcc, s3, v22
	v_lshl_add_u64 v[8:9], v[6:7], 2, v[8:9]
	s_nop 0
	v_addc_co_u32_e32 v27, vcc, 0, v23, vcc
	v_lshl_add_u64 v[28:29], v[8:9], 0, v[128:129]
	v_add_co_u32_e32 v20, vcc, s14, v28
	s_movk_i32 s2, 0x5000
	s_nop 0
	v_addc_co_u32_e32 v21, vcc, 0, v29, vcc
	v_add_co_u32_e32 v30, vcc, s15, v28
	s_nop 1
	v_addc_co_u32_e32 v31, vcc, 0, v29, vcc
	global_load_dword v14, v[16:17], off offset:-4096 nt
	global_load_dword v11, v[16:17], off nt
	global_load_dword v12, v[18:19], off offset:-4096 nt
	global_load_dword v10, v[18:19], off nt
	global_load_dword v8, v[20:21], off offset:-4096 nt
	global_load_dword v3, v[20:21], off nt
	global_load_dword v9, v[30:31], off offset:-4096 nt
	global_load_dword v7, v[30:31], off nt
	v_add_co_u32_e32 v30, vcc, s2, v28
	s_add_u32 s2, s10, 0xfb00000
	s_nop 0
	v_addc_co_u32_e32 v31, vcc, 0, v29, vcc
	v_add_co_u32_e32 v32, vcc, 0x6000, v28
	s_addc_u32 s3, s11, 0
	s_nop 0
	v_addc_co_u32_e32 v33, vcc, 0, v29, vcc
	v_add_co_u32_e32 v34, vcc, 0x7000, v28
	s_nop 1
	v_addc_co_u32_e32 v35, vcc, 0, v29, vcc
	global_load_dword v20, v[22:23], off nt
	global_load_dword v21, v[24:25], off offset:-4096 nt
	global_load_dword v19, v[24:25], off nt
	global_load_dword v18, v[26:27], off nt
	global_load_dword v17, v[28:29], off nt
	global_load_dword v15, v[30:31], off nt
	global_load_dword v13, v[32:33], off nt
	global_load_dword v16, v[34:35], off nt
	v_cmp_gt_i32_e32 vcc, s12, v147
	s_and_saveexec_b64 s[8:9], vcc
	s_cbranch_execnz .LBB0_255
	s_or_b64 exec, exec, s[8:9]
	s_and_saveexec_b64 s[0:1], s[4:5]
	s_cbranch_execnz .LBB0_256

; __device__ __forceinline__ unsigned pk2(float lo, float hi) { unsigned r; asm volatile("v_cvt_pk_bf16_f32 %0, %1, %2" : "=v"(r) : "v"(lo), "v"(hi)); return r; }
; __device__ __forceinline__ unsigned pk2(float lo, float hi) { return f2bf(lo) | (f2bf(hi) << 16); }
; __device__ __forceinline__ void conv_load(const float* src, int stride, float (&v)[8]) {
; #pragma unroll
;     for (int j = 0; j < 8; ++j) v[j] = src[(size_t)j * stride];
; }
; __device__ __forceinline__ void conv_store(bf16_t* dst, const float (&v)[8], const float* kgain, float nscale) {
;     float g[8];
; #pragma unroll
;     for (int j = 0; j < 8; ++j) g[j] = kgain ? kgain[j] * nscale : nscale;
;     u32x4 w; w.x = pk2(v[0] * g[0], v[1] * g[1]); w.y = pk2(v[2] * g[2], v[3] * g[3]); w.z = pk2(v[4] * g[4], v[5] * g[5]); w.w = pk2(v[6] * g[6], v[7] * g[7]);
;     *(u32x4*)dst = w;
; }
.LBB0_253:
	v_mul_hi_i32 v23, v147, s15
	v_lshrrev_b32_e32 v24, 31, v23
	v_ashrrev_i32_e32 v23, 6, v23
	v_add_u32_e32 v23, v23, v24
	v_mul_i32_i24_e32 v24, 0xfffffea0, v23
	v_add_lshl_u32 v24, v24, v147, 3
	v_ashrrev_i32_e32 v25, 31, v24
	v_lshlrev_b64 v[26:27], 12, v[24:25]
	v_lshlrev_b32_e32 v28, 6, v23
	v_lshl_add_u64 v[26:27], s[0:1], 0, v[26:27]
	v_ashrrev_i32_e32 v29, 31, v28
	v_lshl_add_u64 v[26:27], v[28:29], 2, v[26:27]
	v_lshl_add_u64 v[26:27], v[26:27], 0, v[128:129]
	v_add_co_u32_e32 v30, vcc, s16, v26
	v_or_b32_e32 v28, v28, v146
	s_nop 0
	v_addc_co_u32_e32 v31, vcc, 0, v27, vcc
	v_add_co_u32_e32 v32, vcc, s17, v26
	s_nop 1
	v_addc_co_u32_e32 v33, vcc, 0, v27, vcc
	v_add_co_u32_e32 v34, vcc, s18, v26
	s_nop 1
	v_addc_co_u32_e32 v35, vcc, 0, v27, vcc
	v_add_co_u32_e32 v36, vcc, 0x7000, v26
	s_nop 1
	v_addc_co_u32_e32 v37, vcc, 0, v27, vcc
	global_load_dword v23, v[30:31], off offset:-4096 nt
	global_load_dword v38, v[26:27], off nt
	global_load_dword v39, v[30:31], off nt
	global_load_dword v40, v[32:33], off offset:-4096 nt
	global_load_dword v41, v[32:33], off nt
	global_load_dword v42, v[34:35], off offset:-4096 nt
	global_load_dword v43, v[34:35], off nt
	global_load_dword v44, v[36:37], off nt
	v_mov_b64_e32 v[26:27], s[2:3]
	v_mad_i64_i32 v[26:27], s[14:15], v28, s14, v[26:27]
	v_lshl_add_u64 v[28:29], v[24:25], 1, v[26:27]
	s_waitcnt vmcnt(6)
	v_cvt_pk_bf16_f32 v24, v38, v23
	s_waitcnt vmcnt(4)
	v_cvt_pk_bf16_f32 v25, v39, v40
	s_waitcnt vmcnt(2)
	v_cvt_pk_bf16_f32 v26, v41, v42
	s_waitcnt vmcnt(0)
	v_cvt_pk_bf16_f32 v27, v43, v44
	global_store_dwordx4 v[28:29], v[24:27], off
	s_or_b64 exec, exec, s[12:13]
	s_and_saveexec_b64 s[12:13], s[6:7]
	s_cbranch_execz .LBB0_220

; __device__ __forceinline__ unsigned pk2(float lo, float hi) { unsigned r; asm volatile("v_cvt_pk_bf16_f32 %0, %1, %2" : "=v"(r) : "v"(lo), "v"(hi)); return r; }
; __device__ __forceinline__ unsigned pk2(float lo, float hi) { return f2bf(lo) | (f2bf(hi) << 16); }
; __device__ __forceinline__ void conv_load(const float* src, int stride, float (&v)[8]) {
; #pragma unroll
;     for (int j = 0; j < 8; ++j) v[j] = src[(size_t)j * stride];
; }
; __device__ __forceinline__ void conv_store(bf16_t* dst, const float (&v)[8], const float* kgain, float nscale) {
;     float g[8];
; #pragma unroll
;     for (int j = 0; j < 8; ++j) g[j] = kgain ? kgain[j] * nscale : nscale;
;     u32x4 w; w.x = pk2(v[0] * g[0], v[1] * g[1]); w.y = pk2(v[2] * g[2], v[3] * g[3]); w.z = pk2(v[4] * g[4], v[5] * g[5]); w.w = pk2(v[6] * g[6], v[7] * g[7]);
;     *(u32x4*)dst = w;
; }
.LBB0_255:
	v_mul_hi_i32 v22, v147, s13
	v_lshrrev_b32_e32 v23, 31, v22
	v_ashrrev_i32_e32 v22, 6, v22
	v_add_u32_e32 v26, v22, v23
	v_mul_i32_i24_e32 v22, 0xfffffea0, v26
	v_add_lshl_u32 v22, v22, v147, 3
	v_ashrrev_i32_e32 v23, 31, v22
	v_lshlrev_b64 v[24:25], 12, v[22:23]
	v_lshlrev_b32_e32 v26, 6, v26
	v_lshl_add_u64 v[24:25], s[0:1], 0, v[24:25]
	v_ashrrev_i32_e32 v27, 31, v26
	v_lshl_add_u64 v[24:25], v[26:27], 2, v[24:25]
	v_lshl_add_u64 v[24:25], v[24:25], 0, v[128:129]
	v_add_co_u32_e32 v28, vcc, s14, v24
	v_or_b32_e32 v26, v26, v146
	s_nop 0
	v_addc_co_u32_e32 v29, vcc, 0, v25, vcc
	v_add_co_u32_e32 v30, vcc, s15, v24
	s_nop 1
	v_addc_co_u32_e32 v31, vcc, 0, v25, vcc
	v_add_co_u32_e32 v32, vcc, s16, v24
	s_nop 1
	v_addc_co_u32_e32 v33, vcc, 0, v25, vcc
	v_add_co_u32_e32 v34, vcc, 0x7000, v24
	s_nop 1
	v_addc_co_u32_e32 v35, vcc, 0, v25, vcc
	global_load_dword v36, v[28:29], off offset:-4096 nt
	global_load_dword v37, v[24:25], off nt
	global_load_dword v38, v[28:29], off nt
	global_load_dword v39, v[30:31], off offset:-4096 nt
	global_load_dword v40, v[30:31], off nt
	global_load_dword v41, v[32:33], off offset:-4096 nt
	global_load_dword v42, v[32:33], off nt
	global_load_dword v43, v[34:35], off nt
	v_mov_b64_e32 v[24:25], s[2:3]
	v_mad_i64_i32 v[24:25], s[0:1], v26, s12, v[24:25]
	v_lshl_add_u64 v[26:27], v[22:23], 1, v[24:25]
	s_waitcnt vmcnt(0)
	v_cvt_pk_bf16_f32 v22, v37, v36
	v_cvt_pk_bf16_f32 v23, v38, v39
	v_cvt_pk_bf16_f32 v24, v40, v41
	v_cvt_pk_bf16_f32 v25, v42, v43
	global_store_dwordx4 v[26:27], v[22:25], off
	s_or_b64 exec, exec, s[8:9]
	s_and_saveexec_b64 s[0:1], s[4:5]
	s_cbranch_execz .LBB0_239

; __device__ __forceinline__ void conv_addr(const ConvJob& j, int wi, int lane, const float*& src, int& stride, bf16_t*& dst, const float*& kg) {
;     if (j.kind == 1) { const int rb = wi >> 7, k0 = (wi & 127) * 8, pn = rb >> 2, bj = (rb >> 1) & 1;
;         src = j.s0 + (ptrdiff_t)bj * j.d10 + (size_t)k0 * FF + pn * 128 + (rb & 1) * 64 + lane; stride = FF; dst = j.dst + (size_t)(rb * 64 + lane) * D + k0; kg = j.gain + k0; }
; template <int NMAX>
; __device__ __forceinline__ void conv_block(const ConvJob& j, int total, int gw, int NW, int lane) {
;     if (j.kind == 0) return;
;     float v[NMAX][8]; bf16_t* d[NMAX]; const float* kg[NMAX];
; #pragma unroll
;     for (int q = 0; q < NMAX; ++q) { const int wi = gw + q * NW; const float* src; int st;
;         conv_addr(j, wi < total ? wi : gw, lane, src, st, d[q], kg[q]); conv_load(src, st, v[q]); }
.LBB0_331:
	s_cmp_lt_i32 s74, 3
	s_cselect_b64 s[0:1], -1, 0
	s_cmp_gt_i32 s75, 2
	s_cselect_b64 s[2:3], -1, 0
	s_and_b64 s[0:1], s[0:1], s[2:3]
	s_andn2_b64 vcc, exec, s[0:1]
	s_cbranch_vccnz .LBB0_480
	s_mov_b64 s[0:1], s[72:73]
	s_load_dwordx2 s[22:23], s[0:1], 0x10
	s_load_dwordx4 s[16:19], s[0:1], 0x20
	s_load_dwordx2 s[20:21], s[0:1], 0xa0
	s_add_i32 s0, 0, 0x2080c
	v_mov_b32_e32 v0, v220
	v_mov_b32_e32 v1, s0
	ds_read_b32 v1, v1
	v_and_b32_e32 v184, 63, v0
	v_ashrrev_i32_e32 v0, 6, v0
	s_waitcnt lgkmcnt(0)
	s_lshl_b32 s33, s96, 3
	v_lshlrev_b32_e32 v152, 2, v184
	v_lshl_add_u32 v185, v1, 3, v0
	v_and_b32_e32 v0, 1, v1
	v_cmp_eq_u32_e64 s[4:5], 0, v0
	v_add_u32_e32 v187, s33, v185
	v_readfirstlane_b32 s38, v1
	s_and_b64 vcc, exec, s[4:5]
	v_add_u32_e32 v186, s33, v187
	s_cbranch_vccnz .LBB0_341
	s_add_u32 s0, s16, 0xb00000
	s_addc_u32 s1, s17, 0
	s_movk_i32 s35, 0x2c00
	s_sub_u32 s2, s18, s16
	v_cmp_gt_i32_e64 s[6:7], s35, v187
	s_subb_u32 s3, s19, s17
	s_ashr_i64 s[2:3], s[2:3], 2
	v_cndmask_b32_e64 v1, v185, v187, s[6:7]
	v_bfe_u32 v2, v1, 8, 1
	v_lshlrev_b32_e32 v0, 3, v1
	s_waitcnt vmcnt(0)
	v_mul_lo_u32 v3, s3, v2
	v_mul_lo_u32 v2, s2, v2
	v_ashrrev_i32_e32 v4, 2, v1
	v_and_b32_e32 v0, 0x3f8, v0
	v_lshl_add_u64 v[2:3], v[2:3], 2, s[0:1]
	v_and_b32_e32 v4, 0xffffff80, v4
	v_mad_u64_u32 v[2:3], s[8:9], v0, s35, v[2:3]
	v_ashrrev_i32_e32 v5, 31, v4
	v_ashrrev_i32_e32 v1, 1, v1
	v_mov_b32_e32 v153, 0
	v_lshl_add_u64 v[2:3], v[4:5], 2, v[2:3]
	v_lshlrev_b32_e32 v4, 2, v1
	v_and_b32_e32 v4, 0x100, v4
	v_mov_b32_e32 v5, v153
	v_lshl_add_u64 v[2:3], v[2:3], 0, v[4:5]
	v_lshl_add_u64 v[2:3], v[2:3], 0, v[152:153]
	s_movk_i32 s30, 0x2000
	v_add_co_u32_e32 v14, vcc, s30, v2
	s_movk_i32 s34, 0x5000
	s_nop 0
	v_addc_co_u32_e32 v15, vcc, 0, v3, vcc
	v_add_co_u32_e32 v16, vcc, s34, v2
	s_mov_b32 s36, 0x8000
	s_nop 0
	v_addc_co_u32_e32 v17, vcc, 0, v3, vcc
	v_add_co_u32_e32 v18, vcc, s36, v2
	s_mov_b32 s37, 0xb000
	s_nop 0
	v_addc_co_u32_e32 v19, vcc, 0, v3, vcc
	v_add_co_u32_e32 v20, vcc, s37, v2
	s_mov_b32 s39, 0xd000
	s_nop 0
	v_addc_co_u32_e32 v21, vcc, 0, v3, vcc
	v_add_co_u32_e32 v22, vcc, s39, v2
	s_mov_b32 s40, 0x10000
	s_nop 0
	v_addc_co_u32_e32 v23, vcc, 0, v3, vcc
	v_add_co_u32_e32 v24, vcc, s40, v2
	s_mov_b32 s31, 0x13000
	s_nop 0
	v_addc_co_u32_e32 v25, vcc, 0, v3, vcc
	v_add_co_u32_e32 v26, vcc, s31, v2
	v_cmp_gt_i32_e64 s[8:9], s35, v186
	s_nop 0
	v_addc_co_u32_e32 v27, vcc, 0, v3, vcc
	global_load_dword v11, v[2:3], off nt
	global_load_dword v12, v[14:15], off offset:3072 nt
	global_load_dword v8, v[16:17], off offset:2048 nt
	global_load_dword v9, v[18:19], off offset:1024 nt
	global_load_dword v5, v[20:21], off nt
	global_load_dword v6, v[22:23], off offset:3072 nt
	global_load_dword v4, v[24:25], off offset:2048 nt
	global_load_dword v10, v[26:27], off offset:1024 nt
	v_cndmask_b32_e64 v3, v185, v186, s[8:9]
	v_bfe_u32 v7, v3, 8, 1
	v_lshlrev_b32_e32 v2, 3, v3
	v_mul_lo_u32 v15, s3, v7
	v_mul_lo_u32 v14, s2, v7
	v_ashrrev_i32_e32 v7, 2, v3
	v_and_b32_e32 v2, 0x3f8, v2
	v_lshl_add_u64 v[14:15], v[14:15], 2, s[0:1]
	v_and_b32_e32 v16, 0xffffff80, v7
	v_ashrrev_i32_e32 v3, 1, v3
	v_mad_u64_u32 v[14:15], s[10:11], v2, s35, v[14:15]
	v_ashrrev_i32_e32 v17, 31, v16
	v_lshlrev_b32_e32 v7, 2, v3
	v_lshl_add_u64 v[14:15], v[16:17], 2, v[14:15]
	v_and_b32_e32 v16, 0x100, v7
	v_mov_b32_e32 v17, v153
	v_lshl_add_u64 v[14:15], v[14:15], 0, v[16:17]
	v_lshl_add_u64 v[24:25], v[14:15], 0, v[152:153]
	v_add_co_u32_e32 v26, vcc, s30, v24
	v_add_u32_e32 v20, s33, v186
	s_nop 0
	v_addc_co_u32_e32 v27, vcc, 0, v25, vcc
	v_add_co_u32_e32 v28, vcc, s34, v24
	v_cmp_gt_i32_e64 s[10:11], s35, v20
	s_nop 0
	v_addc_co_u32_e32 v29, vcc, 0, v25, vcc
	v_add_co_u32_e32 v30, vcc, s36, v24
	v_cndmask_b32_e64 v13, v185, v20, s[10:11]
	s_nop 0
	v_addc_co_u32_e32 v31, vcc, 0, v25, vcc
	v_add_co_u32_e32 v32, vcc, s37, v24
	v_bfe_u32 v23, v13, 8, 1
	s_nop 0
	v_addc_co_u32_e32 v33, vcc, 0, v25, vcc
	v_add_co_u32_e32 v34, vcc, s39, v24
	v_lshlrev_b32_e32 v7, 3, v13
	s_nop 0
	v_addc_co_u32_e32 v35, vcc, 0, v25, vcc
	v_add_co_u32_e32 v36, vcc, s40, v24
	v_and_b32_e32 v7, 0x3f8, v7
	s_nop 0
	v_addc_co_u32_e32 v37, vcc, 0, v25, vcc
	v_add_co_u32_e32 v38, vcc, s31, v24
	s_add_u32 s26, s22, 0x2000
	s_nop 0
	v_addc_co_u32_e32 v39, vcc, 0, v25, vcc
	global_load_dword v21, v[24:25], off nt
	global_load_dword v22, v[26:27], off offset:3072 nt
	global_load_dword v17, v[28:29], off offset:2048 nt
	global_load_dword v18, v[30:31], off offset:1024 nt
	global_load_dword v15, v[32:33], off nt
	global_load_dword v16, v[34:35], off offset:3072 nt
	global_load_dword v14, v[36:37], off offset:2048 nt
	global_load_dword v19, v[38:39], off offset:1024 nt
	v_mul_lo_u32 v25, s3, v23
	v_mul_lo_u32 v24, s2, v23
	v_ashrrev_i32_e32 v23, 2, v13
	v_lshl_add_u64 v[24:25], v[24:25], 2, s[0:1]
	v_and_b32_e32 v26, 0xffffff80, v23
	v_ashrrev_i32_e32 v13, 1, v13
	v_mad_u64_u32 v[24:25], s[12:13], v7, s35, v[24:25]
	v_ashrrev_i32_e32 v27, 31, v26
; __device__ __forceinline__ void conv_addr(const ConvJob& j, int wi, int lane, const float*& src, int& stride, bf16_t*& dst, const float*& kg) {
;     if (j.kind == 1) { const int rb = wi >> 7, k0 = (wi & 127) * 8, pn = rb >> 2, bj = (rb >> 1) & 1;
;         src = j.s0 + (ptrdiff_t)bj * j.d10 + (size_t)k0 * FF + pn * 128 + (rb & 1) * 64 + lane; stride = FF; dst = j.dst + (size_t)(rb * 64 + lane) * D + k0; kg = j.gain + k0; }
; template <int NMAX>
; __device__ __forceinline__ void conv_block(const ConvJob& j, int total, int gw, int NW, int lane) {
;     if (j.kind == 0) return;
;     float v[NMAX][8]; bf16_t* d[NMAX]; const float* kg[NMAX];
; #pragma unroll
;     for (int q = 0; q < NMAX; ++q) { const int wi = gw + q * NW; const float* src; int st;
;         conv_addr(j, wi < total ? wi : gw, lane, src, st, d[q], kg[q]); conv_load(src, st, v[q]); }
	v_lshlrev_b32_e32 v23, 2, v13
	v_lshl_add_u64 v[24:25], v[26:27], 2, v[24:25]
	v_and_b32_e32 v26, 0x100, v23
	v_mov_b32_e32 v27, v153
	v_lshl_add_u64 v[24:25], v[24:25], 0, v[26:27]
	v_lshl_add_u64 v[34:35], v[24:25], 0, v[152:153]
	v_add_co_u32_e32 v36, vcc, s30, v34
	v_add_u32_e32 v27, s33, v20
	s_nop 0
	v_addc_co_u32_e32 v37, vcc, 0, v35, vcc
	v_add_co_u32_e32 v38, vcc, s34, v34
	v_cmp_gt_i32_e64 s[12:13], s35, v27
	s_nop 0
	v_addc_co_u32_e32 v39, vcc, 0, v35, vcc
	v_add_co_u32_e32 v40, vcc, s36, v34
	v_cndmask_b32_e64 v23, v185, v27, s[12:13]
	s_nop 0
	v_addc_co_u32_e32 v41, vcc, 0, v35, vcc
	v_add_co_u32_e32 v42, vcc, s37, v34
	v_bfe_u32 v33, v23, 8, 1
	s_nop 0
	v_addc_co_u32_e32 v43, vcc, 0, v35, vcc
	v_add_co_u32_e32 v44, vcc, s39, v34
	v_lshlrev_b32_e32 v20, 3, v23
	s_nop 0
	v_addc_co_u32_e32 v45, vcc, 0, v35, vcc
	v_add_co_u32_e32 v46, vcc, s40, v34
	v_and_b32_e32 v20, 0x3f8, v20
	s_nop 0
	v_addc_co_u32_e32 v47, vcc, 0, v35, vcc
	v_add_co_u32_e32 v48, vcc, s31, v34
	v_add_u32_e32 v27, s33, v27
	s_nop 0
	v_addc_co_u32_e32 v49, vcc, 0, v35, vcc
	global_load_dword v31, v[34:35], off nt
	global_load_dword v32, v[36:37], off offset:3072 nt
	global_load_dword v28, v[38:39], off offset:2048 nt
	global_load_dword v29, v[40:41], off offset:1024 nt
	global_load_dword v25, v[42:43], off nt
	global_load_dword v26, v[44:45], off offset:3072 nt
	global_load_dword v24, v[46:47], off offset:2048 nt
	global_load_dword v30, v[48:49], off offset:1024 nt
	v_mul_lo_u32 v35, s3, v33
	v_mul_lo_u32 v34, s2, v33
	v_ashrrev_i32_e32 v33, 2, v23
	v_lshl_add_u64 v[34:35], v[34:35], 2, s[0:1]
	v_and_b32_e32 v36, 0xffffff80, v33
	v_ashrrev_i32_e32 v23, 1, v23
	v_mad_u64_u32 v[34:35], s[14:15], v20, s35, v[34:35]
	v_ashrrev_i32_e32 v37, 31, v36
	v_lshlrev_b32_e32 v33, 2, v23
	v_lshl_add_u64 v[34:35], v[36:37], 2, v[34:35]
	v_and_b32_e32 v36, 0x100, v33
	v_mov_b32_e32 v37, v153
	v_lshl_add_u64 v[34:35], v[34:35], 0, v[36:37]
	v_lshl_add_u64 v[42:43], v[34:35], 0, v[152:153]
	v_add_co_u32_e32 v44, vcc, s30, v42
	v_cmp_gt_i32_e64 s[14:15], s35, v27
	s_nop 0
	v_addc_co_u32_e32 v45, vcc, 0, v43, vcc
	v_add_co_u32_e32 v46, vcc, s34, v42
	v_cndmask_b32_e64 v33, v185, v27, s[14:15]
	s_nop 0
	v_addc_co_u32_e32 v47, vcc, 0, v43, vcc
	v_add_co_u32_e32 v48, vcc, s36, v42
	v_lshlrev_b32_e32 v27, 3, v33
	s_nop 0
	v_addc_co_u32_e32 v49, vcc, 0, v43, vcc
	v_add_co_u32_e32 v50, vcc, s37, v42
	v_and_b32_e32 v27, 0x3f8, v27
	s_nop 0
	v_addc_co_u32_e32 v51, vcc, 0, v43, vcc
	v_add_co_u32_e32 v52, vcc, s39, v42
	s_addc_u32 s27, s23, 0
	s_nop 0
	v_addc_co_u32_e32 v53, vcc, 0, v43, vcc
	v_add_co_u32_e32 v54, vcc, s40, v42
	s_nop 1
	v_addc_co_u32_e32 v55, vcc, 0, v43, vcc
	v_add_co_u32_e32 v56, vcc, s31, v42
	s_nop 1
	v_addc_co_u32_e32 v57, vcc, 0, v43, vcc
	global_load_dword v40, v[42:43], off nt
	global_load_dword v41, v[44:45], off offset:3072 nt
	global_load_dword v37, v[46:47], off offset:2048 nt
	global_load_dword v38, v[48:49], off offset:1024 nt
	global_load_dword v35, v[50:51], off nt
	global_load_dword v36, v[52:53], off offset:3072 nt
	global_load_dword v34, v[54:55], off offset:2048 nt
	global_load_dword v39, v[56:57], off offset:1024 nt
	v_bfe_u32 v42, v33, 8, 1
	v_mul_lo_u32 v43, s3, v42
	v_mul_lo_u32 v42, s2, v42
	v_ashrrev_i32_e32 v44, 2, v33
	v_lshl_add_u64 v[42:43], v[42:43], 2, s[0:1]
	v_and_b32_e32 v44, 0xffffff80, v44
	v_mad_u64_u32 v[42:43], s[24:25], v27, s35, v[42:43]
	v_ashrrev_i32_e32 v45, 31, v44
	v_ashrrev_i32_e32 v33, 1, v33
	v_lshl_add_u64 v[42:43], v[44:45], 2, v[42:43]
	v_lshlrev_b32_e32 v44, 2, v33
	v_and_b32_e32 v44, 0x100, v44
	v_mov_b32_e32 v45, v153
	v_lshl_add_u64 v[42:43], v[42:43], 0, v[44:45]
	v_lshl_add_u64 v[50:51], v[42:43], 0, v[152:153]
	v_add_co_u32_e32 v52, vcc, s30, v50
	s_add_u32 s24, s20, 0xf000000
	s_nop 0
	v_addc_co_u32_e32 v53, vcc, 0, v51, vcc
	v_add_co_u32_e32 v54, vcc, s34, v50
	s_addc_u32 s25, s21, 0
	s_nop 0
	v_addc_co_u32_e32 v55, vcc, 0, v51, vcc
	v_add_co_u32_e32 v56, vcc, s36, v50
	s_nop 1
	v_addc_co_u32_e32 v57, vcc, 0, v51, vcc
	v_add_co_u32_e32 v58, vcc, s37, v50
	s_nop 1
	v_addc_co_u32_e32 v59, vcc, 0, v51, vcc
	v_add_co_u32_e32 v60, vcc, s39, v50
	s_nop 1
	v_addc_co_u32_e32 v61, vcc, 0, v51, vcc
	v_add_co_u32_e32 v62, vcc, 0x10000, v50
	s_nop 1
	v_addc_co_u32_e32 v63, vcc, 0, v51, vcc
	v_add_co_u32_e32 v64, vcc, 0x13000, v50
	s_nop 1
	v_addc_co_u32_e32 v65, vcc, 0, v51, vcc
	global_load_dword v48, v[50:51], off nt
	global_load_dword v49, v[52:53], off offset:3072 nt
	global_load_dword v45, v[54:55], off offset:2048 nt
	global_load_dword v46, v[56:57], off offset:1024 nt
	global_load_dword v43, v[58:59], off nt
	global_load_dword v44, v[60:61], off offset:3072 nt
	global_load_dword v42, v[62:63], off offset:2048 nt
	global_load_dword v47, v[64:65], off offset:1024 nt
	v_cmp_gt_i32_e32 vcc, s35, v185
	s_and_saveexec_b64 s[28:29], vcc
	s_cbranch_execnz .LBB0_396
	s_or_b64 exec, exec, s[28:29]
	s_and_saveexec_b64 s[0:1], s[6:7]
	s_cbranch_execnz .LBB0_397

; __device__ __forceinline__ void conv_addr(const ConvJob& j, int wi, int lane, const float*& src, int& stride, bf16_t*& dst, const float*& kg) {
;     if (j.kind == 1) { const int rb = wi >> 7, k0 = (wi & 127) * 8, pn = rb >> 2, bj = (rb >> 1) & 1;
;         src = j.s0 + (ptrdiff_t)bj * j.d10 + (size_t)k0 * FF + pn * 128 + (rb & 1) * 64 + lane; stride = FF; dst = j.dst + (size_t)(rb * 64 + lane) * D + k0; kg = j.gain + k0; }
; template <int NMAX>
; __device__ __forceinline__ void conv_block(const ConvJob& j, int total, int gw, int NW, int lane) {
;     if (j.kind == 0) return;
;     float v[NMAX][8]; bf16_t* d[NMAX]; const float* kg[NMAX];
; #pragma unroll
;     for (int q = 0; q < NMAX; ++q) { const int wi = gw + q * NW; const float* src; int st;
;         conv_addr(j, wi < total ? wi : gw, lane, src, st, d[q], kg[q]); conv_load(src, st, v[q]); }
.LBB0_377:
	s_add_u32 s0, s16, 0xb00000
	s_addc_u32 s1, s17, 0
	s_movk_i32 s27, 0x2c00
	s_sub_u32 s2, s18, s16
	v_cmp_gt_i32_e64 s[4:5], s27, v187
	s_subb_u32 s3, s19, s17
	s_ashr_i64 s[2:3], s[2:3], 2
	s_waitcnt lgkmcnt(0)
	v_cndmask_b32_e64 v1, v185, v187, s[4:5]
	v_bfe_u32 v2, v1, 8, 1
	v_lshlrev_b32_e32 v0, 3, v1
	v_mul_lo_u32 v3, s3, v2
	v_mul_lo_u32 v2, s2, v2
	v_ashrrev_i32_e32 v4, 2, v1
	v_and_b32_e32 v0, 0x3f8, v0
	v_lshl_add_u64 v[2:3], v[2:3], 2, s[0:1]
	v_and_b32_e32 v4, 0xffffff80, v4
	v_mad_u64_u32 v[2:3], s[6:7], v0, s27, v[2:3]
	v_ashrrev_i32_e32 v5, 31, v4
	v_ashrrev_i32_e32 v1, 1, v1
	v_mov_b32_e32 v153, 0
	v_lshl_add_u64 v[2:3], v[4:5], 2, v[2:3]
	v_lshlrev_b32_e32 v4, 2, v1
	v_and_b32_e32 v4, 0x100, v4
	v_mov_b32_e32 v5, v153
	v_lshl_add_u64 v[2:3], v[2:3], 0, v[4:5]
	v_lshl_add_u64 v[2:3], v[2:3], 0, v[152:153]
	s_movk_i32 s24, 0x2000
	v_add_co_u32_e32 v14, vcc, s24, v2
	s_movk_i32 s26, 0x5000
	s_nop 0
	v_addc_co_u32_e32 v15, vcc, 0, v3, vcc
	v_add_co_u32_e32 v16, vcc, s26, v2
	s_mov_b32 s28, 0x8000
	s_nop 0
	v_addc_co_u32_e32 v17, vcc, 0, v3, vcc
	v_add_co_u32_e32 v18, vcc, s28, v2
	s_mov_b32 s29, 0xb000
	s_nop 0
	v_addc_co_u32_e32 v19, vcc, 0, v3, vcc
	v_add_co_u32_e32 v20, vcc, s29, v2
	s_mov_b32 s30, 0xd000
	s_nop 0
	v_addc_co_u32_e32 v21, vcc, 0, v3, vcc
	v_add_co_u32_e32 v22, vcc, s30, v2
	s_mov_b32 s31, 0x10000
	s_nop 0
	v_addc_co_u32_e32 v23, vcc, 0, v3, vcc
	v_add_co_u32_e32 v24, vcc, s31, v2
	s_mov_b32 s25, 0x13000
	s_nop 0
	v_addc_co_u32_e32 v25, vcc, 0, v3, vcc
	v_add_co_u32_e32 v26, vcc, s25, v2
	v_cmp_gt_i32_e64 s[6:7], s27, v186
	s_nop 0
	v_addc_co_u32_e32 v27, vcc, 0, v3, vcc
	global_load_dword v11, v[2:3], off nt
	global_load_dword v12, v[14:15], off offset:3072 nt
	global_load_dword v8, v[16:17], off offset:2048 nt
	global_load_dword v9, v[18:19], off offset:1024 nt
	global_load_dword v5, v[20:21], off nt
	global_load_dword v6, v[22:23], off offset:3072 nt
	global_load_dword v4, v[24:25], off offset:2048 nt
	global_load_dword v10, v[26:27], off offset:1024 nt
	v_cndmask_b32_e64 v3, v185, v186, s[6:7]
	v_bfe_u32 v7, v3, 8, 1
	v_lshlrev_b32_e32 v2, 3, v3
	v_mul_lo_u32 v15, s3, v7
	v_mul_lo_u32 v14, s2, v7
	v_ashrrev_i32_e32 v7, 2, v3
	v_and_b32_e32 v2, 0x3f8, v2
	v_lshl_add_u64 v[14:15], v[14:15], 2, s[0:1]
	v_and_b32_e32 v16, 0xffffff80, v7
	v_ashrrev_i32_e32 v3, 1, v3
	v_mad_u64_u32 v[14:15], s[8:9], v2, s27, v[14:15]
	v_ashrrev_i32_e32 v17, 31, v16
	v_lshlrev_b32_e32 v7, 2, v3
	v_lshl_add_u64 v[14:15], v[16:17], 2, v[14:15]
	v_and_b32_e32 v16, 0x100, v7
	v_mov_b32_e32 v17, v153
	v_lshl_add_u64 v[14:15], v[14:15], 0, v[16:17]
	v_lshl_add_u64 v[24:25], v[14:15], 0, v[152:153]
	v_add_co_u32_e32 v26, vcc, s24, v24
	v_add_u32_e32 v20, s33, v186
	s_nop 0
	v_addc_co_u32_e32 v27, vcc, 0, v25, vcc
	v_add_co_u32_e32 v28, vcc, s26, v24
	v_cmp_gt_i32_e64 s[8:9], s27, v20
	s_nop 0
	v_addc_co_u32_e32 v29, vcc, 0, v25, vcc
	v_add_co_u32_e32 v30, vcc, s28, v24
	v_cndmask_b32_e64 v13, v185, v20, s[8:9]
	s_nop 0
	v_addc_co_u32_e32 v31, vcc, 0, v25, vcc
	v_add_co_u32_e32 v32, vcc, s29, v24
	v_bfe_u32 v23, v13, 8, 1
	s_nop 0
	v_addc_co_u32_e32 v33, vcc, 0, v25, vcc
	v_add_co_u32_e32 v34, vcc, s30, v24
	v_lshlrev_b32_e32 v7, 3, v13
	s_nop 0
	v_addc_co_u32_e32 v35, vcc, 0, v25, vcc
	v_add_co_u32_e32 v36, vcc, s31, v24
	v_and_b32_e32 v7, 0x3f8, v7
	s_nop 0
	v_addc_co_u32_e32 v37, vcc, 0, v25, vcc
	v_add_co_u32_e32 v38, vcc, s25, v24
	s_add_u32 s16, s22, 0x2000
	s_nop 0
	v_addc_co_u32_e32 v39, vcc, 0, v25, vcc
	global_load_dword v21, v[24:25], off nt
	global_load_dword v22, v[26:27], off offset:3072 nt
	global_load_dword v17, v[28:29], off offset:2048 nt
	global_load_dword v18, v[30:31], off offset:1024 nt
	global_load_dword v15, v[32:33], off nt
	global_load_dword v16, v[34:35], off offset:3072 nt
	global_load_dword v14, v[36:37], off offset:2048 nt
	global_load_dword v19, v[38:39], off offset:1024 nt
	v_mul_lo_u32 v25, s3, v23
	v_mul_lo_u32 v24, s2, v23
	v_ashrrev_i32_e32 v23, 2, v13
	v_lshl_add_u64 v[24:25], v[24:25], 2, s[0:1]
	v_and_b32_e32 v26, 0xffffff80, v23
	v_ashrrev_i32_e32 v13, 1, v13
	v_mad_u64_u32 v[24:25], s[10:11], v7, s27, v[24:25]
	v_ashrrev_i32_e32 v27, 31, v26
	v_lshlrev_b32_e32 v23, 2, v13
	v_lshl_add_u64 v[24:25], v[26:27], 2, v[24:25]
	v_and_b32_e32 v26, 0x100, v23
	v_mov_b32_e32 v27, v153
	v_lshl_add_u64 v[24:25], v[24:25], 0, v[26:27]
	v_lshl_add_u64 v[34:35], v[24:25], 0, v[152:153]
	v_add_co_u32_e32 v36, vcc, s24, v34
	v_add_u32_e32 v27, s33, v20
	s_nop 0
	v_addc_co_u32_e32 v37, vcc, 0, v35, vcc
	v_add_co_u32_e32 v38, vcc, s26, v34
; __device__ __forceinline__ void conv_addr(const ConvJob& j, int wi, int lane, const float*& src, int& stride, bf16_t*& dst, const float*& kg) {
;     if (j.kind == 1) { const int rb = wi >> 7, k0 = (wi & 127) * 8, pn = rb >> 2, bj = (rb >> 1) & 1;
;         src = j.s0 + (ptrdiff_t)bj * j.d10 + (size_t)k0 * FF + pn * 128 + (rb & 1) * 64 + lane; stride = FF; dst = j.dst + (size_t)(rb * 64 + lane) * D + k0; kg = j.gain + k0; }
; template <int NMAX>
; __device__ __forceinline__ void conv_block(const ConvJob& j, int total, int gw, int NW, int lane) {
;     if (j.kind == 0) return;
;     float v[NMAX][8]; bf16_t* d[NMAX]; const float* kg[NMAX];
; #pragma unroll
;     for (int q = 0; q < NMAX; ++q) { const int wi = gw + q * NW; const float* src; int st;
;         conv_addr(j, wi < total ? wi : gw, lane, src, st, d[q], kg[q]); conv_load(src, st, v[q]); }
	v_cmp_gt_i32_e64 s[10:11], s27, v27
	s_nop 0
	v_addc_co_u32_e32 v39, vcc, 0, v35, vcc
	v_add_co_u32_e32 v40, vcc, s28, v34
	v_cndmask_b32_e64 v23, v185, v27, s[10:11]
	s_nop 0
	v_addc_co_u32_e32 v41, vcc, 0, v35, vcc
	v_add_co_u32_e32 v42, vcc, s29, v34
	v_bfe_u32 v33, v23, 8, 1
	s_nop 0
	v_addc_co_u32_e32 v43, vcc, 0, v35, vcc
	v_add_co_u32_e32 v44, vcc, s30, v34
	v_lshlrev_b32_e32 v20, 3, v23
	s_nop 0
	v_addc_co_u32_e32 v45, vcc, 0, v35, vcc
	v_add_co_u32_e32 v46, vcc, s31, v34
	v_and_b32_e32 v20, 0x3f8, v20
	s_nop 0
	v_addc_co_u32_e32 v47, vcc, 0, v35, vcc
	v_add_co_u32_e32 v48, vcc, s25, v34
	v_add_u32_e32 v27, s33, v27
	s_nop 0
	v_addc_co_u32_e32 v49, vcc, 0, v35, vcc
	global_load_dword v31, v[34:35], off nt
	global_load_dword v32, v[36:37], off offset:3072 nt
	global_load_dword v28, v[38:39], off offset:2048 nt
	global_load_dword v29, v[40:41], off offset:1024 nt
	global_load_dword v25, v[42:43], off nt
	global_load_dword v26, v[44:45], off offset:3072 nt
	global_load_dword v24, v[46:47], off offset:2048 nt
	global_load_dword v30, v[48:49], off offset:1024 nt
	v_mul_lo_u32 v35, s3, v33
	v_mul_lo_u32 v34, s2, v33
	v_ashrrev_i32_e32 v33, 2, v23
	v_lshl_add_u64 v[34:35], v[34:35], 2, s[0:1]
	v_and_b32_e32 v36, 0xffffff80, v33
	v_ashrrev_i32_e32 v23, 1, v23
	v_mad_u64_u32 v[34:35], s[12:13], v20, s27, v[34:35]
	v_ashrrev_i32_e32 v37, 31, v36
	v_lshlrev_b32_e32 v33, 2, v23
	v_lshl_add_u64 v[34:35], v[36:37], 2, v[34:35]
	v_and_b32_e32 v36, 0x100, v33
	v_mov_b32_e32 v37, v153
	v_lshl_add_u64 v[34:35], v[34:35], 0, v[36:37]
	v_lshl_add_u64 v[42:43], v[34:35], 0, v[152:153]
	v_add_co_u32_e32 v44, vcc, s24, v42
	v_cmp_gt_i32_e64 s[12:13], s27, v27
	s_nop 0
	v_addc_co_u32_e32 v45, vcc, 0, v43, vcc
	v_add_co_u32_e32 v46, vcc, s26, v42
	v_cndmask_b32_e64 v33, v185, v27, s[12:13]
	s_nop 0
	v_addc_co_u32_e32 v47, vcc, 0, v43, vcc
	v_add_co_u32_e32 v48, vcc, s28, v42
	v_lshlrev_b32_e32 v27, 3, v33
	s_nop 0
	v_addc_co_u32_e32 v49, vcc, 0, v43, vcc
	v_add_co_u32_e32 v50, vcc, s29, v42
	v_and_b32_e32 v27, 0x3f8, v27
	s_nop 0
	v_addc_co_u32_e32 v51, vcc, 0, v43, vcc
	v_add_co_u32_e32 v52, vcc, s30, v42
	s_addc_u32 s17, s23, 0
	s_nop 0
	v_addc_co_u32_e32 v53, vcc, 0, v43, vcc
	v_add_co_u32_e32 v54, vcc, s31, v42
	s_nop 1
	v_addc_co_u32_e32 v55, vcc, 0, v43, vcc
	v_add_co_u32_e32 v56, vcc, s25, v42
	s_nop 1
	v_addc_co_u32_e32 v57, vcc, 0, v43, vcc
	global_load_dword v40, v[42:43], off nt
	global_load_dword v41, v[44:45], off offset:3072 nt
	global_load_dword v37, v[46:47], off offset:2048 nt
	global_load_dword v38, v[48:49], off offset:1024 nt
	global_load_dword v35, v[50:51], off nt
	global_load_dword v36, v[52:53], off offset:3072 nt
	global_load_dword v34, v[54:55], off offset:2048 nt
	global_load_dword v39, v[56:57], off offset:1024 nt
	v_bfe_u32 v42, v33, 8, 1
	v_mul_lo_u32 v43, s3, v42
	v_mul_lo_u32 v42, s2, v42
	v_ashrrev_i32_e32 v44, 2, v33
	v_lshl_add_u64 v[42:43], v[42:43], 2, s[0:1]
	v_and_b32_e32 v44, 0xffffff80, v44
	v_mad_u64_u32 v[42:43], s[14:15], v27, s27, v[42:43]
	v_ashrrev_i32_e32 v45, 31, v44
	v_ashrrev_i32_e32 v33, 1, v33
	v_lshl_add_u64 v[42:43], v[44:45], 2, v[42:43]
	v_lshlrev_b32_e32 v44, 2, v33
	v_and_b32_e32 v44, 0x100, v44
	v_mov_b32_e32 v45, v153
	v_lshl_add_u64 v[42:43], v[42:43], 0, v[44:45]
	v_lshl_add_u64 v[50:51], v[42:43], 0, v[152:153]
	v_add_co_u32_e32 v52, vcc, s24, v50
	s_add_u32 s14, s20, 0xf000000
	s_nop 0
	v_addc_co_u32_e32 v53, vcc, 0, v51, vcc
	v_add_co_u32_e32 v54, vcc, s26, v50
	s_addc_u32 s15, s21, 0
	s_nop 0
	v_addc_co_u32_e32 v55, vcc, 0, v51, vcc
	v_add_co_u32_e32 v56, vcc, s28, v50
	s_nop 1
	v_addc_co_u32_e32 v57, vcc, 0, v51, vcc
	v_add_co_u32_e32 v58, vcc, s29, v50
	s_nop 1
	v_addc_co_u32_e32 v59, vcc, 0, v51, vcc
	v_add_co_u32_e32 v60, vcc, s30, v50
	s_nop 1
	v_addc_co_u32_e32 v61, vcc, 0, v51, vcc
	v_add_co_u32_e32 v62, vcc, 0x10000, v50
	s_nop 1
	v_addc_co_u32_e32 v63, vcc, 0, v51, vcc
	v_add_co_u32_e32 v64, vcc, 0x13000, v50
	s_nop 1
	v_addc_co_u32_e32 v65, vcc, 0, v51, vcc
	global_load_dword v48, v[50:51], off nt
	global_load_dword v49, v[52:53], off offset:3072 nt
	global_load_dword v45, v[54:55], off offset:2048 nt
	global_load_dword v46, v[56:57], off offset:1024 nt
	global_load_dword v43, v[58:59], off nt
	global_load_dword v44, v[60:61], off offset:3072 nt
	global_load_dword v42, v[62:63], off offset:2048 nt
	global_load_dword v47, v[64:65], off offset:1024 nt
	v_cmp_gt_i32_e32 vcc, s27, v185
	s_and_saveexec_b64 s[18:19], vcc
	s_cbranch_execnz .LBB0_401
	s_or_b64 exec, exec, s[18:19]
	s_and_saveexec_b64 s[0:1], s[4:5]
	s_cbranch_execnz .LBB0_402

; __device__ __forceinline__ unsigned pk2(float lo, float hi) { unsigned r; asm volatile("v_cvt_pk_bf16_f32 %0, %1, %2" : "=v"(r) : "v"(lo), "v"(hi)); return r; }
; __device__ __forceinline__ unsigned pk2(float lo, float hi) { return f2bf(lo) | (f2bf(hi) << 16); }
; __device__ __forceinline__ void conv_load(const float* src, int stride, float (&v)[8]) {
; #pragma unroll
;     for (int j = 0; j < 8; ++j) v[j] = src[(size_t)j * stride];
; }
; __device__ __forceinline__ void conv_store(bf16_t* dst, const float (&v)[8], const float* kgain, float nscale) {
;     float g[8];
; #pragma unroll
;     for (int j = 0; j < 8; ++j) g[j] = kgain ? kgain[j] * nscale : nscale;
;     u32x4 w; w.x = pk2(v[0] * g[0], v[1] * g[1]); w.y = pk2(v[2] * g[2], v[3] * g[3]); w.z = pk2(v[4] * g[4], v[5] * g[5]); w.w = pk2(v[6] * g[6], v[7] * g[7]);
;     *(u32x4*)dst = w;
; }
; __device__ __forceinline__ void conv_addr(const ConvJob& j, int wi, int lane, const float*& src, int& stride, bf16_t*& dst, const float*& kg) {
;     if (j.kind == 1) { const int rb = wi >> 7, k0 = (wi & 127) * 8, pn = rb >> 2, bj = (rb >> 1) & 1;
;         src = j.s0 + (ptrdiff_t)bj * j.d10 + (size_t)k0 * FF + pn * 128 + (rb & 1) * 64 + lane; stride = FF; dst = j.dst + (size_t)(rb * 64 + lane) * D + k0; kg = j.gain + k0; }
.LBB0_396:
	v_bfe_u32 v50, v185, 8, 1
	v_lshlrev_b32_e32 v52, 3, v185
	v_mul_lo_u32 v51, s3, v50
	v_mul_lo_u32 v50, s2, v50
	v_and_b32_e32 v64, 0x3f8, v52
	v_ashrrev_i32_e32 v52, 2, v185
	v_lshl_add_u64 v[50:51], v[50:51], 2, s[0:1]
	v_and_b32_e32 v52, 0xffffff80, v52
	v_mad_u64_u32 v[50:51], s[0:1], v64, s35, v[50:51]
	v_ashrrev_i32_e32 v53, 31, v52
	v_ashrrev_i32_e32 v65, 1, v185
	v_lshl_add_u64 v[50:51], v[52:53], 2, v[50:51]
	v_lshlrev_b32_e32 v52, 2, v65
	v_and_b32_e32 v52, 0x100, v52
	v_mov_b32_e32 v53, v153
	v_lshl_add_u64 v[50:51], v[50:51], 0, v[52:53]
	v_lshl_add_u64 v[58:59], v[50:51], 0, v[152:153]
	v_add_co_u32_e32 v50, vcc, s40, v58
	s_movk_i32 s0, 0xffc0
	s_nop 0
	v_addc_co_u32_e32 v51, vcc, 0, v59, vcc
	v_add_co_u32_e32 v52, vcc, s39, v58
	s_nop 1
	v_addc_co_u32_e32 v53, vcc, 0, v59, vcc
	v_add_co_u32_e32 v54, vcc, s37, v58
	s_nop 1
	v_addc_co_u32_e32 v55, vcc, 0, v59, vcc
	v_add_co_u32_e32 v56, vcc, s36, v58
	s_nop 1
	v_addc_co_u32_e32 v57, vcc, 0, v59, vcc
	v_add_co_u32_e32 v60, vcc, s34, v58
	s_nop 1
	v_addc_co_u32_e32 v61, vcc, 0, v59, vcc
	v_add_co_u32_e32 v62, vcc, s30, v58
	s_nop 1
	v_addc_co_u32_e32 v63, vcc, 0, v59, vcc
	global_load_dword v66, v[50:51], off offset:2048 nt
	global_load_dword v67, v[52:53], off offset:3072 nt
	global_load_dword v68, v[54:55], off nt
	global_load_dword v69, v[56:57], off offset:1024 nt
	global_load_dword v70, v[60:61], off offset:2048 nt
	global_load_dword v71, v[62:63], off offset:3072 nt
	global_load_dword v72, v[58:59], off nt
	v_add_co_u32_e32 v58, vcc, s31, v58
	v_lshlrev_b32_e32 v60, 2, v64
	s_nop 0
	v_addc_co_u32_e32 v59, vcc, 0, v59, vcc
	global_load_dwordx4 v[50:53], v60, s[26:27]
	global_load_dwordx4 v[54:57], v60, s[26:27] offset:16
	global_load_dword v62, v[58:59], off offset:1024 nt
	v_and_or_b32 v60, v65, s0, v184
	v_ashrrev_i32_e32 v61, 31, v60
	v_lshlrev_b64 v[60:61], 11, v[60:61]
	v_mov_b32_e32 v59, v153
	v_lshlrev_b32_e32 v58, 1, v64
	v_lshl_add_u64 v[60:61], s[24:25], 0, v[60:61]
	v_lshl_add_u64 v[58:59], v[60:61], 0, v[58:59]
	s_waitcnt vmcnt(2)
	v_mul_f32_e32 v50, v72, v50
	v_mul_f32_e32 v51, v71, v51
	v_mul_f32_e32 v52, v70, v52
	v_mul_f32_e32 v53, v69, v53
	s_waitcnt vmcnt(1)
	v_mul_f32_e32 v54, v68, v54
	v_mul_f32_e32 v55, v67, v55
	v_mul_f32_e32 v56, v66, v56
	s_waitcnt vmcnt(0)
	v_mul_f32_e32 v57, v62, v57
	v_cvt_pk_bf16_f32 v50, v50, v51
	v_cvt_pk_bf16_f32 v51, v52, v53
	v_cvt_pk_bf16_f32 v52, v54, v55
	v_cvt_pk_bf16_f32 v53, v56, v57
	global_store_dwordx4 v[58:59], v[50:53], off
	s_or_b64 exec, exec, s[28:29]
	s_and_saveexec_b64 s[0:1], s[6:7]
	s_cbranch_execz .LBB0_335

; __device__ __forceinline__ unsigned pk2(float lo, float hi) { unsigned r; asm volatile("v_cvt_pk_bf16_f32 %0, %1, %2" : "=v"(r) : "v"(lo), "v"(hi)); return r; }
; __device__ __forceinline__ unsigned pk2(float lo, float hi) { return f2bf(lo) | (f2bf(hi) << 16); }
; __device__ __forceinline__ void conv_load(const float* src, int stride, float (&v)[8]) {
; #pragma unroll
;     for (int j = 0; j < 8; ++j) v[j] = src[(size_t)j * stride];
; }
; __device__ __forceinline__ void conv_store(bf16_t* dst, const float (&v)[8], const float* kgain, float nscale) {
;     float g[8];
; #pragma unroll
;     for (int j = 0; j < 8; ++j) g[j] = kgain ? kgain[j] * nscale : nscale;
;     u32x4 w; w.x = pk2(v[0] * g[0], v[1] * g[1]); w.y = pk2(v[2] * g[2], v[3] * g[3]); w.z = pk2(v[4] * g[4], v[5] * g[5]); w.w = pk2(v[6] * g[6], v[7] * g[7]);
;     *(u32x4*)dst = w;
; }
; __device__ __forceinline__ void conv_addr(const ConvJob& j, int wi, int lane, const float*& src, int& stride, bf16_t*& dst, const float*& kg) {
;     if (j.kind == 1) { const int rb = wi >> 7, k0 = (wi & 127) * 8, pn = rb >> 2, bj = (rb >> 1) & 1;
;         src = j.s0 + (ptrdiff_t)bj * j.d10 + (size_t)k0 * FF + pn * 128 + (rb & 1) * 64 + lane; stride = FF; dst = j.dst + (size_t)(rb * 64 + lane) * D + k0; kg = j.gain + k0; }
.LBB0_401:
	v_bfe_u32 v50, v185, 8, 1
	v_lshlrev_b32_e32 v52, 3, v185
	v_mul_lo_u32 v51, s3, v50
	v_mul_lo_u32 v50, s2, v50
	v_and_b32_e32 v64, 0x3f8, v52
	v_ashrrev_i32_e32 v52, 2, v185
	v_lshl_add_u64 v[50:51], v[50:51], 2, s[0:1]
	v_and_b32_e32 v52, 0xffffff80, v52
	v_mad_u64_u32 v[50:51], s[0:1], v64, s27, v[50:51]
	v_ashrrev_i32_e32 v53, 31, v52
	v_ashrrev_i32_e32 v65, 1, v185
	v_lshl_add_u64 v[50:51], v[52:53], 2, v[50:51]
	v_lshlrev_b32_e32 v52, 2, v65
	v_and_b32_e32 v52, 0x100, v52
	v_mov_b32_e32 v53, v153
	v_lshl_add_u64 v[50:51], v[50:51], 0, v[52:53]
	v_lshl_add_u64 v[58:59], v[50:51], 0, v[152:153]
	v_add_co_u32_e32 v50, vcc, s31, v58
	s_movk_i32 s0, 0xffc0
	s_nop 0
	v_addc_co_u32_e32 v51, vcc, 0, v59, vcc
	v_add_co_u32_e32 v52, vcc, s30, v58
	v_lshlrev_b32_e32 v152, 1, v64
	s_nop 0
	v_addc_co_u32_e32 v53, vcc, 0, v59, vcc
	v_add_co_u32_e32 v54, vcc, s29, v58
	s_nop 1
	v_addc_co_u32_e32 v55, vcc, 0, v59, vcc
	v_add_co_u32_e32 v56, vcc, s28, v58
	s_nop 1
	v_addc_co_u32_e32 v57, vcc, 0, v59, vcc
	v_add_co_u32_e32 v60, vcc, s26, v58
	s_nop 1
	v_addc_co_u32_e32 v61, vcc, 0, v59, vcc
	v_add_co_u32_e32 v62, vcc, s24, v58
	s_nop 1
	v_addc_co_u32_e32 v63, vcc, 0, v59, vcc
	global_load_dword v66, v[50:51], off offset:2048 nt
	global_load_dword v67, v[52:53], off offset:3072 nt
	global_load_dword v68, v[54:55], off nt
	global_load_dword v69, v[56:57], off offset:1024 nt
	global_load_dword v70, v[60:61], off offset:2048 nt
	global_load_dword v71, v[62:63], off offset:3072 nt
	global_load_dword v72, v[58:59], off nt
	v_add_co_u32_e32 v58, vcc, s25, v58
	v_lshlrev_b32_e32 v60, 2, v64
	s_nop 0
	v_addc_co_u32_e32 v59, vcc, 0, v59, vcc
	global_load_dwordx4 v[50:53], v60, s[16:17]
	global_load_dwordx4 v[54:57], v60, s[16:17] offset:16
	s_waitcnt vmcnt(1)
	v_mul_f32_e32 v50, v72, v50
	global_load_dword v60, v[58:59], off offset:1024 nt
	v_and_or_b32 v58, v65, s0, v184
	v_ashrrev_i32_e32 v59, 31, v58
	v_lshlrev_b64 v[58:59], 11, v[58:59]
	v_lshl_add_u64 v[58:59], s[14:15], 0, v[58:59]
	v_lshl_add_u64 v[58:59], v[58:59], 0, v[152:153]
	v_mul_f32_e32 v51, v71, v51
	v_mul_f32_e32 v52, v70, v52
	v_mul_f32_e32 v53, v69, v53
	s_waitcnt vmcnt(1)
	v_mul_f32_e32 v54, v68, v54
	v_mul_f32_e32 v55, v67, v55
	v_mul_f32_e32 v56, v66, v56
	v_cvt_pk_bf16_f32 v50, v50, v51
	v_cvt_pk_bf16_f32 v51, v52, v53
	v_cvt_pk_bf16_f32 v52, v54, v55
	s_waitcnt vmcnt(0)
	v_mul_f32_e32 v57, v60, v57
	v_cvt_pk_bf16_f32 v53, v56, v57
	global_store_dwordx4 v[58:59], v[50:53], off
	s_or_b64 exec, exec, s[18:19]
	s_and_saveexec_b64 s[0:1], s[4:5]
	s_cbranch_execz .LBB0_379

; template <int NMAX>
; __device__ __forceinline__ void conv_block(const ConvJob& j, int total, int gw, int NW, int lane) {
;     if (j.kind == 0) return;
;     float v[NMAX][8]; bf16_t* d[NMAX]; const float* kg[NMAX];
; #pragma unroll
;     for (int q = 0; q < NMAX; ++q) { const int wi = gw + q * NW; const float* src; int st;
;         conv_addr(j, wi < total ? wi : gw, lane, src, st, d[q], kg[q]); conv_load(src, st, v[q]); }
.LBB0_1026:
	s_cmp_lt_i32 s74, 9
	s_cselect_b64 s[0:1], -1, 0
	s_cmp_gt_i32 s75, 8
	s_cselect_b64 s[2:3], -1, 0
	s_and_b64 s[0:1], s[0:1], s[2:3]
	s_andn2_b64 vcc, exec, s[0:1]
	s_cbranch_vccnz .LBB0_1141
	s_mov_b64 s[2:3], s[72:73]
	s_load_dwordx2 s[0:1], s[2:3], 0x30
	s_load_dwordx2 s[10:11], s[2:3], 0xa0
	s_add_i32 s2, 0, 0x2080c
	s_waitcnt vmcnt(0)
	v_mov_b32_e32 v8, v220
	v_mov_b32_e32 v0, s2
	ds_read_b32 v0, v0
	s_waitcnt lgkmcnt(0)
	v_ashrrev_i32_e32 v1, 6, v8
	s_lshl_b32 s2, s96, 3
	v_and_b32_e32 v146, 63, v8
	v_lshlrev_b32_e32 v128, 2, v146
	v_readfirstlane_b32 s33, v0
	v_lshl_add_u32 v147, v0, 3, v1
	v_and_b32_e32 v0, 1, v0
	v_cmp_eq_u32_e64 s[4:5], 0, v0
	v_add_u32_e32 v149, s2, v147
	s_and_b64 vcc, exec, s[4:5]
	v_add_u32_e32 v148, s2, v149
	s_cbranch_vccnz .LBB0_1033
	s_movk_i32 s16, 0x1600
	v_cmp_gt_i32_e64 s[6:7], s16, v149
	s_mov_b32 s17, 0x2e8ba2e9
	s_add_u32 s2, s0, 0xb00000
	v_cndmask_b32_e64 v0, v147, v149, s[6:7]
	v_mul_hi_i32 v1, v0, s17
	v_lshrrev_b32_e32 v2, 31, v1
	v_ashrrev_i32_e32 v1, 6, v1
	v_add_u32_e32 v6, v1, v2
	v_mul_i32_i24_e32 v1, 0xfffffea0, v6
	v_add_lshl_u32 v0, v1, v0, 3
	v_ashrrev_i32_e32 v1, 31, v0
	s_addc_u32 s3, s1, 0
	v_lshlrev_b64 v[2:3], 12, v[0:1]
	v_lshl_add_u64 v[4:5], s[2:3], 0, v[2:3]
	v_lshlrev_b32_e32 v2, 6, v6
	v_ashrrev_i32_e32 v3, 31, v2
	v_mov_b32_e32 v129, 0
	v_lshl_add_u64 v[4:5], v[2:3], 2, v[4:5]
	v_lshl_add_u64 v[24:25], v[4:5], 0, v[128:129]
	s_movk_i32 s18, 0x2000
	v_add_co_u32_e32 v26, vcc, s18, v24
	s_movk_i32 s19, 0x4000
	s_nop 0
	v_addc_co_u32_e32 v27, vcc, 0, v25, vcc
	v_add_co_u32_e32 v16, vcc, s19, v24
	s_movk_i32 s20, 0x6000
	s_nop 0
	v_addc_co_u32_e32 v17, vcc, 0, v25, vcc
	v_add_co_u32_e32 v18, vcc, s20, v24
	s_movk_i32 s8, 0x7000
	s_nop 0
	v_addc_co_u32_e32 v19, vcc, 0, v25, vcc
	v_add_co_u32_e32 v28, vcc, s8, v24
	v_cmp_gt_i32_e64 s[8:9], s16, v148
	s_nop 0
	v_addc_co_u32_e32 v29, vcc, 0, v25, vcc
	v_cndmask_b32_e64 v3, v147, v148, s[8:9]
	v_mul_hi_i32 v4, v3, s17
	v_lshrrev_b32_e32 v5, 31, v4
	v_ashrrev_i32_e32 v4, 6, v4
	v_add_u32_e32 v9, v4, v5
	v_mul_i32_i24_e32 v4, 0xfffffea0, v9
	v_add_lshl_u32 v4, v4, v3, 3
	v_ashrrev_i32_e32 v5, 31, v4
	v_lshlrev_b64 v[6:7], 12, v[4:5]
	v_lshl_add_u64 v[10:11], s[2:3], 0, v[6:7]
	v_lshlrev_b32_e32 v6, 6, v9
	v_ashrrev_i32_e32 v7, 31, v6
	v_lshl_add_u64 v[10:11], v[6:7], 2, v[10:11]
	v_lshl_add_u64 v[30:31], v[10:11], 0, v[128:129]
	v_add_co_u32_e32 v20, vcc, s18, v30
	s_movk_i32 s12, 0x5000
	s_nop 0
	v_addc_co_u32_e32 v21, vcc, 0, v31, vcc
	v_add_co_u32_e32 v22, vcc, s19, v30
	s_nop 1
	v_addc_co_u32_e32 v23, vcc, 0, v31, vcc
	v_add_co_u32_e32 v32, vcc, s12, v30
	global_load_dword v15, v[16:17], off offset:-4096 nt
	global_load_dword v12, v[16:17], off nt
	global_load_dword v13, v[18:19], off offset:-4096 nt
	global_load_dword v11, v[18:19], off nt
	global_load_dword v9, v[20:21], off offset:-4096 nt
	global_load_dword v3, v[20:21], off nt
	global_load_dword v10, v[22:23], off offset:-4096 nt
	global_load_dword v7, v[22:23], off nt
	v_addc_co_u32_e32 v33, vcc, 0, v31, vcc
	v_add_co_u32_e32 v34, vcc, 0x6000, v30
	s_add_u32 s12, s10, 0xfb00000
	s_nop 0
	v_addc_co_u32_e32 v35, vcc, 0, v31, vcc
	v_add_co_u32_e32 v36, vcc, 0x7000, v30
	s_addc_u32 s13, s11, 0
	s_nop 0
	v_addc_co_u32_e32 v37, vcc, 0, v31, vcc
	global_load_dword v21, v[24:25], off nt
	global_load_dword v22, v[26:27], off offset:-4096 nt
	global_load_dword v20, v[26:27], off nt
	global_load_dword v19, v[28:29], off nt
	global_load_dword v18, v[30:31], off nt
	global_load_dword v16, v[32:33], off nt
	global_load_dword v14, v[34:35], off nt
	global_load_dword v17, v[36:37], off nt
	v_cmp_gt_i32_e32 vcc, s16, v147
	s_and_saveexec_b64 s[14:15], vcc
	s_cbranch_execnz .LBB0_1063
	s_or_b64 exec, exec, s[14:15]
	s_and_saveexec_b64 s[2:3], s[6:7]
	s_cbranch_execnz .LBB0_1064

; __device__ __forceinline__ void conv_addr(const ConvJob& j, int wi, int lane, const float*& src, int& stride, bf16_t*& dst, const float*& kg) {
;     ...
;     else { const int nb = wi / 352, k0 = (wi - nb * 352) * 8;
;         src = j.s0 + (size_t)k0 * D + nb * 64 + lane; stride = D; dst = j.dst + (size_t)(nb * 64 + lane) * FF + k0; kg = nullptr; }
; template <int NMAX>
; __device__ __forceinline__ void conv_block(const ConvJob& j, int total, int gw, int NW, int lane) {
;     if (j.kind == 0) return;
;     float v[NMAX][8]; bf16_t* d[NMAX]; const float* kg[NMAX];
; #pragma unroll
;     for (int q = 0; q < NMAX; ++q) { const int wi = gw + q * NW; const float* src; int st;
;         conv_addr(j, wi < total ? wi : gw, lane, src, st, d[q], kg[q]); conv_load(src, st, v[q]); }
.LBB0_1047:
	s_movk_i32 s12, 0x1600
	v_cmp_gt_i32_e64 s[4:5], s12, v149
	s_mov_b32 s13, 0x2e8ba2e9
	s_add_u32 s0, s0, 0xb00000
	v_cndmask_b32_e64 v0, v147, v149, s[4:5]
	v_mul_hi_i32 v1, v0, s13
	v_lshrrev_b32_e32 v2, 31, v1
	v_ashrrev_i32_e32 v1, 6, v1
	v_add_u32_e32 v6, v1, v2
	v_mul_i32_i24_e32 v1, 0xfffffea0, v6
	v_add_lshl_u32 v0, v1, v0, 3
	v_ashrrev_i32_e32 v1, 31, v0
	s_addc_u32 s1, s1, 0
	v_lshlrev_b64 v[2:3], 12, v[0:1]
	v_lshl_add_u64 v[4:5], s[0:1], 0, v[2:3]
	v_lshlrev_b32_e32 v2, 6, v6
	v_ashrrev_i32_e32 v3, 31, v2
	v_cmp_gt_i32_e64 s[6:7], s12, v148
	v_mov_b32_e32 v129, 0
	v_lshl_add_u64 v[4:5], v[2:3], 2, v[4:5]
	v_cndmask_b32_e64 v3, v147, v148, s[6:7]
	v_lshl_add_u64 v[22:23], v[4:5], 0, v[128:129]
	v_mul_hi_i32 v4, v3, s13
	v_lshrrev_b32_e32 v5, 31, v4
	v_ashrrev_i32_e32 v4, 6, v4
	s_movk_i32 s14, 0x2000
	v_add_u32_e32 v10, v4, v5
	v_add_co_u32_e32 v24, vcc, s14, v22
	v_mul_i32_i24_e32 v4, 0xfffffea0, v10
	s_nop 0
	v_addc_co_u32_e32 v25, vcc, 0, v23, vcc
	s_movk_i32 s15, 0x4000
	v_add_lshl_u32 v4, v4, v3, 3
	v_add_co_u32_e32 v16, vcc, s15, v22
	v_ashrrev_i32_e32 v5, 31, v4
	s_nop 0
	v_addc_co_u32_e32 v17, vcc, 0, v23, vcc
	s_movk_i32 s16, 0x6000
	v_lshlrev_b64 v[6:7], 12, v[4:5]
	v_add_co_u32_e32 v18, vcc, s16, v22
	v_lshl_add_u64 v[8:9], s[0:1], 0, v[6:7]
	v_lshlrev_b32_e32 v6, 6, v10
	v_addc_co_u32_e32 v19, vcc, 0, v23, vcc
	s_movk_i32 s3, 0x7000
	v_ashrrev_i32_e32 v7, 31, v6
	v_add_co_u32_e32 v26, vcc, s3, v22
	v_lshl_add_u64 v[8:9], v[6:7], 2, v[8:9]
	s_nop 0
	v_addc_co_u32_e32 v27, vcc, 0, v23, vcc
	v_lshl_add_u64 v[28:29], v[8:9], 0, v[128:129]
	v_add_co_u32_e32 v20, vcc, s14, v28
	s_movk_i32 s2, 0x5000
	s_nop 0
	v_addc_co_u32_e32 v21, vcc, 0, v29, vcc
	v_add_co_u32_e32 v30, vcc, s15, v28
	s_nop 1
	v_addc_co_u32_e32 v31, vcc, 0, v29, vcc
	global_load_dword v14, v[16:17], off offset:-4096 nt
	global_load_dword v11, v[16:17], off nt
	global_load_dword v12, v[18:19], off offset:-4096 nt
	global_load_dword v10, v[18:19], off nt
	global_load_dword v8, v[20:21], off offset:-4096 nt
	global_load_dword v3, v[20:21], off nt
	global_load_dword v9, v[30:31], off offset:-4096 nt
	global_load_dword v7, v[30:31], off nt
	v_add_co_u32_e32 v30, vcc, s2, v28
	s_add_u32 s2, s10, 0xfb00000
	s_nop 0
	v_addc_co_u32_e32 v31, vcc, 0, v29, vcc
	v_add_co_u32_e32 v32, vcc, 0x6000, v28
	s_addc_u32 s3, s11, 0
	s_nop 0
	v_addc_co_u32_e32 v33, vcc, 0, v29, vcc
	v_add_co_u32_e32 v34, vcc, 0x7000, v28
	s_nop 1
	v_addc_co_u32_e32 v35, vcc, 0, v29, vcc
	global_load_dword v20, v[22:23], off nt
	global_load_dword v21, v[24:25], off offset:-4096 nt
	global_load_dword v19, v[24:25], off nt
	global_load_dword v18, v[26:27], off nt
	global_load_dword v17, v[28:29], off nt
	global_load_dword v15, v[30:31], off nt
	global_load_dword v13, v[32:33], off nt
	global_load_dword v16, v[34:35], off nt
	v_cmp_gt_i32_e32 vcc, s12, v147
	s_and_saveexec_b64 s[8:9], vcc
	s_cbranch_execnz .LBB0_1065
	s_or_b64 exec, exec, s[8:9]
	s_and_saveexec_b64 s[0:1], s[4:5]
	s_cbranch_execnz .LBB0_1066

; __device__ __forceinline__ unsigned pk2(float lo, float hi) { unsigned r; asm volatile("v_cvt_pk_bf16_f32 %0, %1, %2" : "=v"(r) : "v"(lo), "v"(hi)); return r; }
; __device__ __forceinline__ unsigned pk2(float lo, float hi) { return f2bf(lo) | (f2bf(hi) << 16); }
; __device__ __forceinline__ void conv_load(const float* src, int stride, float (&v)[8]) {
; #pragma unroll
;     for (int j = 0; j < 8; ++j) v[j] = src[(size_t)j * stride];
; }
; __device__ __forceinline__ void conv_store(bf16_t* dst, const float (&v)[8], const float* kgain, float nscale) {
;     float g[8];
; #pragma unroll
;     for (int j = 0; j < 8; ++j) g[j] = kgain ? kgain[j] * nscale : nscale;
;     u32x4 w; w.x = pk2(v[0] * g[0], v[1] * g[1]); w.y = pk2(v[2] * g[2], v[3] * g[3]); w.z = pk2(v[4] * g[4], v[5] * g[5]); w.w = pk2(v[6] * g[6], v[7] * g[7]);
;     *(u32x4*)dst = w;
; }
; __device__ __forceinline__ void conv_addr(const ConvJob& j, int wi, int lane, const float*& src, int& stride, bf16_t*& dst, const float*& kg) {
;     if (j.kind == 1) { const int rb = wi >> 7, k0 = (wi & 127) * 8, pn = rb >> 2, bj = (rb >> 1) & 1;
;         src = j.s0 + (ptrdiff_t)bj * j.d10 + (size_t)k0 * FF + pn * 128 + (rb & 1) * 64 + lane; stride = FF; dst = j.dst + (size_t)(rb * 64 + lane) * D + k0; kg = j.gain + k0; }
;     else { const int nb = wi / 352, k0 = (wi - nb * 352) * 8;
;         src = j.s0 + (size_t)k0 * D + nb * 64 + lane; stride = D; dst = j.dst + (size_t)(nb * 64 + lane) * FF + k0; kg = nullptr; }
.LBB0_1063:
	v_mul_hi_i32 v23, v147, s17
	v_lshrrev_b32_e32 v24, 31, v23
	v_ashrrev_i32_e32 v23, 6, v23
	v_add_u32_e32 v23, v23, v24
	v_mul_i32_i24_e32 v24, 0xfffffea0, v23
	v_add_lshl_u32 v24, v24, v147, 3
	v_ashrrev_i32_e32 v25, 31, v24
	v_lshlrev_b64 v[26:27], 12, v[24:25]
	v_lshlrev_b32_e32 v28, 6, v23
	v_lshl_add_u64 v[26:27], s[2:3], 0, v[26:27]
	v_ashrrev_i32_e32 v29, 31, v28
	v_lshl_add_u64 v[26:27], v[28:29], 2, v[26:27]
	v_lshl_add_u64 v[26:27], v[26:27], 0, v[128:129]
	v_add_co_u32_e32 v30, vcc, s18, v26
	v_or_b32_e32 v28, v28, v146
	s_nop 0
	v_addc_co_u32_e32 v31, vcc, 0, v27, vcc
	v_add_co_u32_e32 v32, vcc, s19, v26
	s_nop 1
	v_addc_co_u32_e32 v33, vcc, 0, v27, vcc
	v_add_co_u32_e32 v34, vcc, s20, v26
	s_nop 1
	v_addc_co_u32_e32 v35, vcc, 0, v27, vcc
	v_add_co_u32_e32 v36, vcc, 0x7000, v26
	s_nop 1
	v_addc_co_u32_e32 v37, vcc, 0, v27, vcc
	global_load_dword v23, v[30:31], off offset:-4096 nt
	global_load_dword v38, v[26:27], off nt
	global_load_dword v39, v[30:31], off nt
	global_load_dword v40, v[32:33], off offset:-4096 nt
	global_load_dword v41, v[32:33], off nt
	global_load_dword v42, v[34:35], off offset:-4096 nt
	global_load_dword v43, v[34:35], off nt
	global_load_dword v44, v[36:37], off nt
	v_mov_b64_e32 v[26:27], s[12:13]
	v_mad_i64_i32 v[26:27], s[2:3], v28, s16, v[26:27]
	v_lshl_add_u64 v[28:29], v[24:25], 1, v[26:27]
	s_waitcnt vmcnt(6)
	v_cvt_pk_bf16_f32 v24, v38, v23
	s_waitcnt vmcnt(4)
	v_cvt_pk_bf16_f32 v25, v39, v40
	s_waitcnt vmcnt(2)
	v_cvt_pk_bf16_f32 v26, v41, v42
	s_waitcnt vmcnt(0)
	v_cvt_pk_bf16_f32 v27, v43, v44
	global_store_dwordx4 v[28:29], v[24:27], off
	s_or_b64 exec, exec, s[14:15]
	s_and_saveexec_b64 s[2:3], s[6:7]
	s_cbranch_execz .LBB0_1030

; __device__ __forceinline__ void conv_addr(const ConvJob& j, int wi, int lane, const float*& src, int& stride, bf16_t*& dst, const float*& kg) {
;     if (j.kind == 1) { const int rb = wi >> 7, k0 = (wi & 127) * 8, pn = rb >> 2, bj = (rb >> 1) & 1;
;         src = j.s0 + (ptrdiff_t)bj * j.d10 + (size_t)k0 * FF + pn * 128 + (rb & 1) * 64 + lane; stride = FF; dst = j.dst + (size_t)(rb * 64 + lane) * D + k0; kg = j.gain + k0; }
; template <int NMAX>
; __device__ __forceinline__ void conv_block(const ConvJob& j, int total, int gw, int NW, int lane) {
;     if (j.kind == 0) return;
;     float v[NMAX][8]; bf16_t* d[NMAX]; const float* kg[NMAX];
; #pragma unroll
;     for (int q = 0; q < NMAX; ++q) { const int wi = gw + q * NW; const float* src; int st;
;         conv_addr(j, wi < total ? wi : gw, lane, src, st, d[q], kg[q]); conv_load(src, st, v[q]); }
.LBB0_1141:
	s_cmp_lt_i32 s74, 10
	s_cselect_b64 s[0:1], -1, 0
	s_cmp_gt_i32 s75, 9
	s_cselect_b64 s[2:3], -1, 0
	s_and_b64 s[0:1], s[0:1], s[2:3]
	s_andn2_b64 vcc, exec, s[0:1]
	s_cbranch_vccnz .LBB0_1290
	s_mov_b64 s[0:1], s[72:73]
	s_load_dwordx2 s[22:23], s[0:1], 0x10
	s_load_dwordx4 s[16:19], s[0:1], 0x20
	s_load_dwordx2 s[20:21], s[0:1], 0xa0
	s_add_i32 s0, 0, 0x2080c
	v_mov_b32_e32 v0, v220
	s_waitcnt lgkmcnt(0)
	v_mov_b32_e32 v1, s0
	ds_read_b32 v1, v1
	v_and_b32_e32 v184, 63, v0
	v_ashrrev_i32_e32 v0, 6, v0
	s_lshl_b32 s33, s96, 3
	v_lshlrev_b32_e32 v152, 2, v184
	s_waitcnt lgkmcnt(0)
	v_lshl_add_u32 v185, v1, 3, v0
	v_and_b32_e32 v0, 1, v1
	v_cmp_eq_u32_e64 s[4:5], 0, v0
	v_add_u32_e32 v187, s33, v185
	v_readfirstlane_b32 s38, v1
	s_and_b64 vcc, exec, s[4:5]
	v_add_u32_e32 v186, s33, v187
	s_cbranch_vccnz .LBB0_1151
	s_add_u32 s0, s16, 0x1600000
	s_addc_u32 s1, s17, 0
	s_movk_i32 s35, 0x2c00
	s_sub_u32 s2, s18, s16
	v_cmp_gt_i32_e64 s[6:7], s35, v187
	s_subb_u32 s3, s19, s17
	s_ashr_i64 s[2:3], s[2:3], 2
	v_cndmask_b32_e64 v1, v185, v187, s[6:7]
	v_bfe_u32 v2, v1, 8, 1
	v_lshlrev_b32_e32 v0, 3, v1
	s_waitcnt vmcnt(0)
	v_mul_lo_u32 v3, s3, v2
	v_mul_lo_u32 v2, s2, v2
	v_ashrrev_i32_e32 v4, 2, v1
	v_and_b32_e32 v0, 0x3f8, v0
	v_lshl_add_u64 v[2:3], v[2:3], 2, s[0:1]
	v_and_b32_e32 v4, 0xffffff80, v4
	v_mad_u64_u32 v[2:3], s[8:9], v0, s35, v[2:3]
	v_ashrrev_i32_e32 v5, 31, v4
	v_ashrrev_i32_e32 v1, 1, v1
	v_mov_b32_e32 v153, 0
	v_lshl_add_u64 v[2:3], v[4:5], 2, v[2:3]
	v_lshlrev_b32_e32 v4, 2, v1
	v_and_b32_e32 v4, 0x100, v4
	v_mov_b32_e32 v5, v153
	v_lshl_add_u64 v[2:3], v[2:3], 0, v[4:5]
	v_lshl_add_u64 v[2:3], v[2:3], 0, v[152:153]
	s_movk_i32 s30, 0x2000
	v_add_co_u32_e32 v14, vcc, s30, v2
	s_movk_i32 s34, 0x5000
	s_nop 0
	v_addc_co_u32_e32 v15, vcc, 0, v3, vcc
	v_add_co_u32_e32 v16, vcc, s34, v2
	s_mov_b32 s36, 0x8000
	s_nop 0
	v_addc_co_u32_e32 v17, vcc, 0, v3, vcc
	v_add_co_u32_e32 v18, vcc, s36, v2
	s_mov_b32 s37, 0xb000
	s_nop 0
	v_addc_co_u32_e32 v19, vcc, 0, v3, vcc
	v_add_co_u32_e32 v20, vcc, s37, v2
	s_mov_b32 s39, 0xd000
	s_nop 0
	v_addc_co_u32_e32 v21, vcc, 0, v3, vcc
	v_add_co_u32_e32 v22, vcc, s39, v2
	s_mov_b32 s40, 0x10000
	s_nop 0
	v_addc_co_u32_e32 v23, vcc, 0, v3, vcc
	v_add_co_u32_e32 v24, vcc, s40, v2
	s_mov_b32 s31, 0x13000
	s_nop 0
	v_addc_co_u32_e32 v25, vcc, 0, v3, vcc
	v_add_co_u32_e32 v26, vcc, s31, v2
	v_cmp_gt_i32_e64 s[8:9], s35, v186
	s_nop 0
	v_addc_co_u32_e32 v27, vcc, 0, v3, vcc
	global_load_dword v11, v[2:3], off nt
	global_load_dword v12, v[14:15], off offset:3072 nt
	global_load_dword v8, v[16:17], off offset:2048 nt
	global_load_dword v9, v[18:19], off offset:1024 nt
	global_load_dword v5, v[20:21], off nt
	global_load_dword v6, v[22:23], off offset:3072 nt
	global_load_dword v4, v[24:25], off offset:2048 nt
	global_load_dword v10, v[26:27], off offset:1024 nt
	v_cndmask_b32_e64 v3, v185, v186, s[8:9]
	v_bfe_u32 v7, v3, 8, 1
	v_lshlrev_b32_e32 v2, 3, v3
	v_mul_lo_u32 v15, s3, v7
	v_mul_lo_u32 v14, s2, v7
	v_ashrrev_i32_e32 v7, 2, v3
	v_and_b32_e32 v2, 0x3f8, v2
	v_lshl_add_u64 v[14:15], v[14:15], 2, s[0:1]
	v_and_b32_e32 v16, 0xffffff80, v7
	v_ashrrev_i32_e32 v3, 1, v3
	v_mad_u64_u32 v[14:15], s[10:11], v2, s35, v[14:15]
	v_ashrrev_i32_e32 v17, 31, v16
	v_lshlrev_b32_e32 v7, 2, v3
	v_lshl_add_u64 v[14:15], v[16:17], 2, v[14:15]
	v_and_b32_e32 v16, 0x100, v7
	v_mov_b32_e32 v17, v153
	v_lshl_add_u64 v[14:15], v[14:15], 0, v[16:17]
	v_lshl_add_u64 v[24:25], v[14:15], 0, v[152:153]
	v_add_co_u32_e32 v26, vcc, s30, v24
	v_add_u32_e32 v20, s33, v186
	s_nop 0
	v_addc_co_u32_e32 v27, vcc, 0, v25, vcc
	v_add_co_u32_e32 v28, vcc, s34, v24
	v_cmp_gt_i32_e64 s[10:11], s35, v20
	s_nop 0
	v_addc_co_u32_e32 v29, vcc, 0, v25, vcc
	v_add_co_u32_e32 v30, vcc, s36, v24
	v_cndmask_b32_e64 v13, v185, v20, s[10:11]
	s_nop 0
	v_addc_co_u32_e32 v31, vcc, 0, v25, vcc
	v_add_co_u32_e32 v32, vcc, s37, v24
	v_bfe_u32 v23, v13, 8, 1
	s_nop 0
	v_addc_co_u32_e32 v33, vcc, 0, v25, vcc
	v_add_co_u32_e32 v34, vcc, s39, v24
	v_lshlrev_b32_e32 v7, 3, v13
	s_nop 0
	v_addc_co_u32_e32 v35, vcc, 0, v25, vcc
	v_add_co_u32_e32 v36, vcc, s40, v24
	v_and_b32_e32 v7, 0x3f8, v7
	s_nop 0
	v_addc_co_u32_e32 v37, vcc, 0, v25, vcc
	v_add_co_u32_e32 v38, vcc, s31, v24
	s_add_u32 s26, s22, 0x3000
	s_nop 0
	v_addc_co_u32_e32 v39, vcc, 0, v25, vcc
	global_load_dword v21, v[24:25], off nt
	global_load_dword v22, v[26:27], off offset:3072 nt
	global_load_dword v17, v[28:29], off offset:2048 nt
	global_load_dword v18, v[30:31], off offset:1024 nt
	global_load_dword v15, v[32:33], off nt
	global_load_dword v16, v[34:35], off offset:3072 nt
	global_load_dword v14, v[36:37], off offset:2048 nt
	global_load_dword v19, v[38:39], off offset:1024 nt
	v_mul_lo_u32 v25, s3, v23
	v_mul_lo_u32 v24, s2, v23
	v_ashrrev_i32_e32 v23, 2, v13
	v_lshl_add_u64 v[24:25], v[24:25], 2, s[0:1]
	v_and_b32_e32 v26, 0xffffff80, v23
	v_ashrrev_i32_e32 v13, 1, v13
	v_mad_u64_u32 v[24:25], s[12:13], v7, s35, v[24:25]
; __device__ __forceinline__ void conv_addr(const ConvJob& j, int wi, int lane, const float*& src, int& stride, bf16_t*& dst, const float*& kg) {
;     if (j.kind == 1) { const int rb = wi >> 7, k0 = (wi & 127) * 8, pn = rb >> 2, bj = (rb >> 1) & 1;
;         src = j.s0 + (ptrdiff_t)bj * j.d10 + (size_t)k0 * FF + pn * 128 + (rb & 1) * 64 + lane; stride = FF; dst = j.dst + (size_t)(rb * 64 + lane) * D + k0; kg = j.gain + k0; }
; template <int NMAX>
; __device__ __forceinline__ void conv_block(const ConvJob& j, int total, int gw, int NW, int lane) {
;     if (j.kind == 0) return;
;     float v[NMAX][8]; bf16_t* d[NMAX]; const float* kg[NMAX];
; #pragma unroll
;     for (int q = 0; q < NMAX; ++q) { const int wi = gw + q * NW; const float* src; int st;
;         conv_addr(j, wi < total ? wi : gw, lane, src, st, d[q], kg[q]); conv_load(src, st, v[q]); }
	v_ashrrev_i32_e32 v27, 31, v26
	v_lshlrev_b32_e32 v23, 2, v13
	v_lshl_add_u64 v[24:25], v[26:27], 2, v[24:25]
	v_and_b32_e32 v26, 0x100, v23
	v_mov_b32_e32 v27, v153
	v_lshl_add_u64 v[24:25], v[24:25], 0, v[26:27]
	v_lshl_add_u64 v[34:35], v[24:25], 0, v[152:153]
	v_add_co_u32_e32 v36, vcc, s30, v34
	v_add_u32_e32 v27, s33, v20
	s_nop 0
	v_addc_co_u32_e32 v37, vcc, 0, v35, vcc
	v_add_co_u32_e32 v38, vcc, s34, v34
	v_cmp_gt_i32_e64 s[12:13], s35, v27
	s_nop 0
	v_addc_co_u32_e32 v39, vcc, 0, v35, vcc
	v_add_co_u32_e32 v40, vcc, s36, v34
	v_cndmask_b32_e64 v23, v185, v27, s[12:13]
	s_nop 0
	v_addc_co_u32_e32 v41, vcc, 0, v35, vcc
	v_add_co_u32_e32 v42, vcc, s37, v34
	v_bfe_u32 v33, v23, 8, 1
	s_nop 0
	v_addc_co_u32_e32 v43, vcc, 0, v35, vcc
	v_add_co_u32_e32 v44, vcc, s39, v34
	v_lshlrev_b32_e32 v20, 3, v23
	s_nop 0
	v_addc_co_u32_e32 v45, vcc, 0, v35, vcc
	v_add_co_u32_e32 v46, vcc, s40, v34
	v_and_b32_e32 v20, 0x3f8, v20
	s_nop 0
	v_addc_co_u32_e32 v47, vcc, 0, v35, vcc
	v_add_co_u32_e32 v48, vcc, s31, v34
	v_add_u32_e32 v27, s33, v27
	s_nop 0
	v_addc_co_u32_e32 v49, vcc, 0, v35, vcc
	global_load_dword v31, v[34:35], off nt
	global_load_dword v32, v[36:37], off offset:3072 nt
	global_load_dword v28, v[38:39], off offset:2048 nt
	global_load_dword v29, v[40:41], off offset:1024 nt
	global_load_dword v25, v[42:43], off nt
	global_load_dword v26, v[44:45], off offset:3072 nt
	global_load_dword v24, v[46:47], off offset:2048 nt
	global_load_dword v30, v[48:49], off offset:1024 nt
	v_mul_lo_u32 v35, s3, v33
	v_mul_lo_u32 v34, s2, v33
	v_ashrrev_i32_e32 v33, 2, v23
	v_lshl_add_u64 v[34:35], v[34:35], 2, s[0:1]
	v_and_b32_e32 v36, 0xffffff80, v33
	v_ashrrev_i32_e32 v23, 1, v23
	v_mad_u64_u32 v[34:35], s[14:15], v20, s35, v[34:35]
	v_ashrrev_i32_e32 v37, 31, v36
	v_lshlrev_b32_e32 v33, 2, v23
	v_lshl_add_u64 v[34:35], v[36:37], 2, v[34:35]
	v_and_b32_e32 v36, 0x100, v33
	v_mov_b32_e32 v37, v153
	v_lshl_add_u64 v[34:35], v[34:35], 0, v[36:37]
	v_lshl_add_u64 v[42:43], v[34:35], 0, v[152:153]
	v_add_co_u32_e32 v44, vcc, s30, v42
	v_cmp_gt_i32_e64 s[14:15], s35, v27
	s_nop 0
	v_addc_co_u32_e32 v45, vcc, 0, v43, vcc
	v_add_co_u32_e32 v46, vcc, s34, v42
	v_cndmask_b32_e64 v33, v185, v27, s[14:15]
	s_nop 0
	v_addc_co_u32_e32 v47, vcc, 0, v43, vcc
	v_add_co_u32_e32 v48, vcc, s36, v42
	v_lshlrev_b32_e32 v27, 3, v33
	s_nop 0
	v_addc_co_u32_e32 v49, vcc, 0, v43, vcc
	v_add_co_u32_e32 v50, vcc, s37, v42
	v_and_b32_e32 v27, 0x3f8, v27
	s_nop 0
	v_addc_co_u32_e32 v51, vcc, 0, v43, vcc
	v_add_co_u32_e32 v52, vcc, s39, v42
	s_addc_u32 s27, s23, 0
	s_nop 0
	v_addc_co_u32_e32 v53, vcc, 0, v43, vcc
	v_add_co_u32_e32 v54, vcc, s40, v42
	s_nop 1
	v_addc_co_u32_e32 v55, vcc, 0, v43, vcc
	v_add_co_u32_e32 v56, vcc, s31, v42
	s_nop 1
	v_addc_co_u32_e32 v57, vcc, 0, v43, vcc
	global_load_dword v40, v[42:43], off nt
	global_load_dword v41, v[44:45], off offset:3072 nt
	global_load_dword v37, v[46:47], off offset:2048 nt
	global_load_dword v38, v[48:49], off offset:1024 nt
	global_load_dword v35, v[50:51], off nt
	global_load_dword v36, v[52:53], off offset:3072 nt
	global_load_dword v34, v[54:55], off offset:2048 nt
	global_load_dword v39, v[56:57], off offset:1024 nt
	v_bfe_u32 v42, v33, 8, 1
	v_mul_lo_u32 v43, s3, v42
	v_mul_lo_u32 v42, s2, v42
	v_ashrrev_i32_e32 v44, 2, v33
	v_lshl_add_u64 v[42:43], v[42:43], 2, s[0:1]
	v_and_b32_e32 v44, 0xffffff80, v44
	v_mad_u64_u32 v[42:43], s[24:25], v27, s35, v[42:43]
	v_ashrrev_i32_e32 v45, 31, v44
	v_ashrrev_i32_e32 v33, 1, v33
	v_lshl_add_u64 v[42:43], v[44:45], 2, v[42:43]
	v_lshlrev_b32_e32 v44, 2, v33
	v_and_b32_e32 v44, 0x100, v44
	v_mov_b32_e32 v45, v153
	v_lshl_add_u64 v[42:43], v[42:43], 0, v[44:45]
	v_lshl_add_u64 v[50:51], v[42:43], 0, v[152:153]
	v_add_co_u32_e32 v52, vcc, s30, v50
	s_add_u32 s24, s20, 0xf000000
	s_nop 0
	v_addc_co_u32_e32 v53, vcc, 0, v51, vcc
	v_add_co_u32_e32 v54, vcc, s34, v50
	s_addc_u32 s25, s21, 0
	s_nop 0
	v_addc_co_u32_e32 v55, vcc, 0, v51, vcc
	v_add_co_u32_e32 v56, vcc, s36, v50
	s_nop 1
	v_addc_co_u32_e32 v57, vcc, 0, v51, vcc
	v_add_co_u32_e32 v58, vcc, s37, v50
	s_nop 1
	v_addc_co_u32_e32 v59, vcc, 0, v51, vcc
	v_add_co_u32_e32 v60, vcc, s39, v50
	s_nop 1
	v_addc_co_u32_e32 v61, vcc, 0, v51, vcc
	v_add_co_u32_e32 v62, vcc, 0x10000, v50
	s_nop 1
	v_addc_co_u32_e32 v63, vcc, 0, v51, vcc
	v_add_co_u32_e32 v64, vcc, 0x13000, v50
	s_nop 1
	v_addc_co_u32_e32 v65, vcc, 0, v51, vcc
	global_load_dword v48, v[50:51], off nt
	global_load_dword v49, v[52:53], off offset:3072 nt
	global_load_dword v45, v[54:55], off offset:2048 nt
	global_load_dword v46, v[56:57], off offset:1024 nt
	global_load_dword v43, v[58:59], off nt
	global_load_dword v44, v[60:61], off offset:3072 nt
	global_load_dword v42, v[62:63], off offset:2048 nt
	global_load_dword v47, v[64:65], off offset:1024 nt
	v_cmp_gt_i32_e32 vcc, s35, v185
	s_and_saveexec_b64 s[28:29], vcc
	s_cbranch_execnz .LBB0_1206
	s_or_b64 exec, exec, s[28:29]
	s_and_saveexec_b64 s[0:1], s[6:7]
	s_cbranch_execnz .LBB0_1207

; __device__ __forceinline__ void conv_addr(const ConvJob& j, int wi, int lane, const float*& src, int& stride, bf16_t*& dst, const float*& kg) {
;     if (j.kind == 1) { const int rb = wi >> 7, k0 = (wi & 127) * 8, pn = rb >> 2, bj = (rb >> 1) & 1;
;         src = j.s0 + (ptrdiff_t)bj * j.d10 + (size_t)k0 * FF + pn * 128 + (rb & 1) * 64 + lane; stride = FF; dst = j.dst + (size_t)(rb * 64 + lane) * D + k0; kg = j.gain + k0; }
; template <int NMAX>
; __device__ __forceinline__ void conv_block(const ConvJob& j, int total, int gw, int NW, int lane) {
;     if (j.kind == 0) return;
;     float v[NMAX][8]; bf16_t* d[NMAX]; const float* kg[NMAX];
; #pragma unroll
;     for (int q = 0; q < NMAX; ++q) { const int wi = gw + q * NW; const float* src; int st;
;         conv_addr(j, wi < total ? wi : gw, lane, src, st, d[q], kg[q]); conv_load(src, st, v[q]); }
.LBB0_1187:
	s_add_u32 s0, s16, 0x1600000
	s_addc_u32 s1, s17, 0
	s_movk_i32 s27, 0x2c00
	s_sub_u32 s2, s18, s16
	v_cmp_gt_i32_e64 s[4:5], s27, v187
	s_subb_u32 s3, s19, s17
	s_ashr_i64 s[2:3], s[2:3], 2
	s_waitcnt lgkmcnt(0)
	v_cndmask_b32_e64 v1, v185, v187, s[4:5]
	v_bfe_u32 v2, v1, 8, 1
	v_lshlrev_b32_e32 v0, 3, v1
	v_mul_lo_u32 v3, s3, v2
	v_mul_lo_u32 v2, s2, v2
	v_ashrrev_i32_e32 v4, 2, v1
	v_and_b32_e32 v0, 0x3f8, v0
	v_lshl_add_u64 v[2:3], v[2:3], 2, s[0:1]
	v_and_b32_e32 v4, 0xffffff80, v4
	v_mad_u64_u32 v[2:3], s[6:7], v0, s27, v[2:3]
	v_ashrrev_i32_e32 v5, 31, v4
	v_ashrrev_i32_e32 v1, 1, v1
	v_mov_b32_e32 v153, 0
	v_lshl_add_u64 v[2:3], v[4:5], 2, v[2:3]
	v_lshlrev_b32_e32 v4, 2, v1
	v_and_b32_e32 v4, 0x100, v4
	v_mov_b32_e32 v5, v153
	v_lshl_add_u64 v[2:3], v[2:3], 0, v[4:5]
	v_lshl_add_u64 v[2:3], v[2:3], 0, v[152:153]
	s_movk_i32 s24, 0x2000
	v_add_co_u32_e32 v14, vcc, s24, v2
	s_movk_i32 s26, 0x5000
	s_nop 0
	v_addc_co_u32_e32 v15, vcc, 0, v3, vcc
	v_add_co_u32_e32 v16, vcc, s26, v2
	s_mov_b32 s28, 0x8000
	s_nop 0
	v_addc_co_u32_e32 v17, vcc, 0, v3, vcc
	v_add_co_u32_e32 v18, vcc, s28, v2
	s_mov_b32 s29, 0xb000
	s_nop 0
	v_addc_co_u32_e32 v19, vcc, 0, v3, vcc
	v_add_co_u32_e32 v20, vcc, s29, v2
	s_mov_b32 s30, 0xd000
	s_nop 0
	v_addc_co_u32_e32 v21, vcc, 0, v3, vcc
	v_add_co_u32_e32 v22, vcc, s30, v2
	s_mov_b32 s31, 0x10000
	s_nop 0
	v_addc_co_u32_e32 v23, vcc, 0, v3, vcc
	v_add_co_u32_e32 v24, vcc, s31, v2
	s_mov_b32 s25, 0x13000
	s_nop 0
	v_addc_co_u32_e32 v25, vcc, 0, v3, vcc
	v_add_co_u32_e32 v26, vcc, s25, v2
	v_cmp_gt_i32_e64 s[6:7], s27, v186
	s_nop 0
	v_addc_co_u32_e32 v27, vcc, 0, v3, vcc
	global_load_dword v11, v[2:3], off nt
	global_load_dword v12, v[14:15], off offset:3072 nt
	global_load_dword v8, v[16:17], off offset:2048 nt
	global_load_dword v9, v[18:19], off offset:1024 nt
	global_load_dword v5, v[20:21], off nt
	global_load_dword v6, v[22:23], off offset:3072 nt
	global_load_dword v4, v[24:25], off offset:2048 nt
	global_load_dword v10, v[26:27], off offset:1024 nt
	v_cndmask_b32_e64 v3, v185, v186, s[6:7]
	v_bfe_u32 v7, v3, 8, 1
	v_lshlrev_b32_e32 v2, 3, v3
	v_mul_lo_u32 v15, s3, v7
	v_mul_lo_u32 v14, s2, v7
	v_ashrrev_i32_e32 v7, 2, v3
	v_and_b32_e32 v2, 0x3f8, v2
	v_lshl_add_u64 v[14:15], v[14:15], 2, s[0:1]
	v_and_b32_e32 v16, 0xffffff80, v7
	v_ashrrev_i32_e32 v3, 1, v3
	v_mad_u64_u32 v[14:15], s[8:9], v2, s27, v[14:15]
	v_ashrrev_i32_e32 v17, 31, v16
	v_lshlrev_b32_e32 v7, 2, v3
	v_lshl_add_u64 v[14:15], v[16:17], 2, v[14:15]
	v_and_b32_e32 v16, 0x100, v7
	v_mov_b32_e32 v17, v153
	v_lshl_add_u64 v[14:15], v[14:15], 0, v[16:17]
	v_lshl_add_u64 v[24:25], v[14:15], 0, v[152:153]
	v_add_co_u32_e32 v26, vcc, s24, v24
	v_add_u32_e32 v20, s33, v186
	s_nop 0
	v_addc_co_u32_e32 v27, vcc, 0, v25, vcc
	v_add_co_u32_e32 v28, vcc, s26, v24
	v_cmp_gt_i32_e64 s[8:9], s27, v20
	s_nop 0
	v_addc_co_u32_e32 v29, vcc, 0, v25, vcc
	v_add_co_u32_e32 v30, vcc, s28, v24
	v_cndmask_b32_e64 v13, v185, v20, s[8:9]
	s_nop 0
	v_addc_co_u32_e32 v31, vcc, 0, v25, vcc
	v_add_co_u32_e32 v32, vcc, s29, v24
	v_bfe_u32 v23, v13, 8, 1
	s_nop 0
	v_addc_co_u32_e32 v33, vcc, 0, v25, vcc
	v_add_co_u32_e32 v34, vcc, s30, v24
	v_lshlrev_b32_e32 v7, 3, v13
	s_nop 0
	v_addc_co_u32_e32 v35, vcc, 0, v25, vcc
	v_add_co_u32_e32 v36, vcc, s31, v24
	v_and_b32_e32 v7, 0x3f8, v7
	s_nop 0
	v_addc_co_u32_e32 v37, vcc, 0, v25, vcc
	v_add_co_u32_e32 v38, vcc, s25, v24
	s_add_u32 s16, s22, 0x3000
	s_nop 0
	v_addc_co_u32_e32 v39, vcc, 0, v25, vcc
	global_load_dword v21, v[24:25], off nt
	global_load_dword v22, v[26:27], off offset:3072 nt
	global_load_dword v17, v[28:29], off offset:2048 nt
	global_load_dword v18, v[30:31], off offset:1024 nt
	global_load_dword v15, v[32:33], off nt
	global_load_dword v16, v[34:35], off offset:3072 nt
	global_load_dword v14, v[36:37], off offset:2048 nt
	global_load_dword v19, v[38:39], off offset:1024 nt
	v_mul_lo_u32 v25, s3, v23
	v_mul_lo_u32 v24, s2, v23
	v_ashrrev_i32_e32 v23, 2, v13
	v_lshl_add_u64 v[24:25], v[24:25], 2, s[0:1]
	v_and_b32_e32 v26, 0xffffff80, v23
	v_ashrrev_i32_e32 v13, 1, v13
	v_mad_u64_u32 v[24:25], s[10:11], v7, s27, v[24:25]
	v_ashrrev_i32_e32 v27, 31, v26
	v_lshlrev_b32_e32 v23, 2, v13
	v_lshl_add_u64 v[24:25], v[26:27], 2, v[24:25]
	v_and_b32_e32 v26, 0x100, v23
	v_mov_b32_e32 v27, v153
	v_lshl_add_u64 v[24:25], v[24:25], 0, v[26:27]
	v_lshl_add_u64 v[34:35], v[24:25], 0, v[152:153]
	v_add_co_u32_e32 v36, vcc, s24, v34
	v_add_u32_e32 v27, s33, v20
	s_nop 0
	v_addc_co_u32_e32 v37, vcc, 0, v35, vcc
	v_add_co_u32_e32 v38, vcc, s26, v34
; __device__ __forceinline__ void conv_addr(const ConvJob& j, int wi, int lane, const float*& src, int& stride, bf16_t*& dst, const float*& kg) {
;     if (j.kind == 1) { const int rb = wi >> 7, k0 = (wi & 127) * 8, pn = rb >> 2, bj = (rb >> 1) & 1;
;         src = j.s0 + (ptrdiff_t)bj * j.d10 + (size_t)k0 * FF + pn * 128 + (rb & 1) * 64 + lane; stride = FF; dst = j.dst + (size_t)(rb * 64 + lane) * D + k0; kg = j.gain + k0; }
; template <int NMAX>
; __device__ __forceinline__ void conv_block(const ConvJob& j, int total, int gw, int NW, int lane) {
;     if (j.kind == 0) return;
;     float v[NMAX][8]; bf16_t* d[NMAX]; const float* kg[NMAX];
; #pragma unroll
;     for (int q = 0; q < NMAX; ++q) { const int wi = gw + q * NW; const float* src; int st;
;         conv_addr(j, wi < total ? wi : gw, lane, src, st, d[q], kg[q]); conv_load(src, st, v[q]); }
	v_cmp_gt_i32_e64 s[10:11], s27, v27
	s_nop 0
	v_addc_co_u32_e32 v39, vcc, 0, v35, vcc
	v_add_co_u32_e32 v40, vcc, s28, v34
	v_cndmask_b32_e64 v23, v185, v27, s[10:11]
	s_nop 0
	v_addc_co_u32_e32 v41, vcc, 0, v35, vcc
	v_add_co_u32_e32 v42, vcc, s29, v34
	v_bfe_u32 v33, v23, 8, 1
	s_nop 0
	v_addc_co_u32_e32 v43, vcc, 0, v35, vcc
	v_add_co_u32_e32 v44, vcc, s30, v34
	v_lshlrev_b32_e32 v20, 3, v23
	s_nop 0
	v_addc_co_u32_e32 v45, vcc, 0, v35, vcc
	v_add_co_u32_e32 v46, vcc, s31, v34
	v_and_b32_e32 v20, 0x3f8, v20
	s_nop 0
	v_addc_co_u32_e32 v47, vcc, 0, v35, vcc
	v_add_co_u32_e32 v48, vcc, s25, v34
	v_add_u32_e32 v27, s33, v27
	s_nop 0
	v_addc_co_u32_e32 v49, vcc, 0, v35, vcc
	global_load_dword v31, v[34:35], off nt
	global_load_dword v32, v[36:37], off offset:3072 nt
	global_load_dword v28, v[38:39], off offset:2048 nt
	global_load_dword v29, v[40:41], off offset:1024 nt
	global_load_dword v25, v[42:43], off nt
	global_load_dword v26, v[44:45], off offset:3072 nt
	global_load_dword v24, v[46:47], off offset:2048 nt
	global_load_dword v30, v[48:49], off offset:1024 nt
	v_mul_lo_u32 v35, s3, v33
	v_mul_lo_u32 v34, s2, v33
	v_ashrrev_i32_e32 v33, 2, v23
	v_lshl_add_u64 v[34:35], v[34:35], 2, s[0:1]
	v_and_b32_e32 v36, 0xffffff80, v33
	v_ashrrev_i32_e32 v23, 1, v23
	v_mad_u64_u32 v[34:35], s[12:13], v20, s27, v[34:35]
	v_ashrrev_i32_e32 v37, 31, v36
	v_lshlrev_b32_e32 v33, 2, v23
	v_lshl_add_u64 v[34:35], v[36:37], 2, v[34:35]
	v_and_b32_e32 v36, 0x100, v33
	v_mov_b32_e32 v37, v153
	v_lshl_add_u64 v[34:35], v[34:35], 0, v[36:37]
	v_lshl_add_u64 v[42:43], v[34:35], 0, v[152:153]
	v_add_co_u32_e32 v44, vcc, s24, v42
	v_cmp_gt_i32_e64 s[12:13], s27, v27
	s_nop 0
	v_addc_co_u32_e32 v45, vcc, 0, v43, vcc
	v_add_co_u32_e32 v46, vcc, s26, v42
	v_cndmask_b32_e64 v33, v185, v27, s[12:13]
	s_nop 0
	v_addc_co_u32_e32 v47, vcc, 0, v43, vcc
	v_add_co_u32_e32 v48, vcc, s28, v42
	v_lshlrev_b32_e32 v27, 3, v33
	s_nop 0
	v_addc_co_u32_e32 v49, vcc, 0, v43, vcc
	v_add_co_u32_e32 v50, vcc, s29, v42
	v_and_b32_e32 v27, 0x3f8, v27
	s_nop 0
	v_addc_co_u32_e32 v51, vcc, 0, v43, vcc
	v_add_co_u32_e32 v52, vcc, s30, v42
	s_addc_u32 s17, s23, 0
	s_nop 0
	v_addc_co_u32_e32 v53, vcc, 0, v43, vcc
	v_add_co_u32_e32 v54, vcc, s31, v42
	s_nop 1
	v_addc_co_u32_e32 v55, vcc, 0, v43, vcc
	v_add_co_u32_e32 v56, vcc, s25, v42
	s_nop 1
	v_addc_co_u32_e32 v57, vcc, 0, v43, vcc
	global_load_dword v40, v[42:43], off nt
	global_load_dword v41, v[44:45], off offset:3072 nt
	global_load_dword v37, v[46:47], off offset:2048 nt
	global_load_dword v38, v[48:49], off offset:1024 nt
	global_load_dword v35, v[50:51], off nt
	global_load_dword v36, v[52:53], off offset:3072 nt
	global_load_dword v34, v[54:55], off offset:2048 nt
	global_load_dword v39, v[56:57], off offset:1024 nt
	v_bfe_u32 v42, v33, 8, 1
	v_mul_lo_u32 v43, s3, v42
	v_mul_lo_u32 v42, s2, v42
	v_ashrrev_i32_e32 v44, 2, v33
	v_lshl_add_u64 v[42:43], v[42:43], 2, s[0:1]
	v_and_b32_e32 v44, 0xffffff80, v44
	v_mad_u64_u32 v[42:43], s[14:15], v27, s27, v[42:43]
	v_ashrrev_i32_e32 v45, 31, v44
	v_ashrrev_i32_e32 v33, 1, v33
	v_lshl_add_u64 v[42:43], v[44:45], 2, v[42:43]
	v_lshlrev_b32_e32 v44, 2, v33
	v_and_b32_e32 v44, 0x100, v44
	v_mov_b32_e32 v45, v153
	v_lshl_add_u64 v[42:43], v[42:43], 0, v[44:45]
	v_lshl_add_u64 v[50:51], v[42:43], 0, v[152:153]
	v_add_co_u32_e32 v52, vcc, s24, v50
	s_add_u32 s14, s20, 0xf000000
	s_nop 0
	v_addc_co_u32_e32 v53, vcc, 0, v51, vcc
	v_add_co_u32_e32 v54, vcc, s26, v50
	s_addc_u32 s15, s21, 0
	s_nop 0
	v_addc_co_u32_e32 v55, vcc, 0, v51, vcc
	v_add_co_u32_e32 v56, vcc, s28, v50
	s_nop 1
	v_addc_co_u32_e32 v57, vcc, 0, v51, vcc
	v_add_co_u32_e32 v58, vcc, s29, v50
	s_nop 1
	v_addc_co_u32_e32 v59, vcc, 0, v51, vcc
	v_add_co_u32_e32 v60, vcc, s30, v50
	s_nop 1
	v_addc_co_u32_e32 v61, vcc, 0, v51, vcc
	v_add_co_u32_e32 v62, vcc, 0x10000, v50
	s_nop 1
	v_addc_co_u32_e32 v63, vcc, 0, v51, vcc
	v_add_co_u32_e32 v64, vcc, 0x13000, v50
	s_nop 1
	v_addc_co_u32_e32 v65, vcc, 0, v51, vcc
	global_load_dword v48, v[50:51], off nt
	global_load_dword v49, v[52:53], off offset:3072 nt
	global_load_dword v45, v[54:55], off offset:2048 nt
	global_load_dword v46, v[56:57], off offset:1024 nt
	global_load_dword v43, v[58:59], off nt
	global_load_dword v44, v[60:61], off offset:3072 nt
	global_load_dword v42, v[62:63], off offset:2048 nt
	global_load_dword v47, v[64:65], off offset:1024 nt
	v_cmp_gt_i32_e32 vcc, s27, v185
	s_and_saveexec_b64 s[18:19], vcc
	s_cbranch_execnz .LBB0_1211
	s_or_b64 exec, exec, s[18:19]
	s_and_saveexec_b64 s[0:1], s[4:5]
	s_cbranch_execnz .LBB0_1212

; __device__ __forceinline__ void conv_addr(const ConvJob& j, int wi, int lane, const float*& src, int& stride, bf16_t*& dst, const float*& kg) {
;     ...
;     else { const int nb = wi / 352, k0 = (wi - nb * 352) * 8;
;         src = j.s0 + (size_t)k0 * D + nb * 64 + lane; stride = D; dst = j.dst + (size_t)(nb * 64 + lane) * FF + k0; kg = nullptr; }
; template <int NMAX>
; __device__ __forceinline__ void conv_block(const ConvJob& j, int total, int gw, int NW, int lane) {
;     if (j.kind == 0) return;
;     float v[NMAX][8]; bf16_t* d[NMAX]; const float* kg[NMAX];
; #pragma unroll
;     for (int q = 0; q < NMAX; ++q) { const int wi = gw + q * NW; const float* src; int st;
;         conv_addr(j, wi < total ? wi : gw, lane, src, st, d[q], kg[q]); conv_load(src, st, v[q]); }
.LBB0_1290:
	s_cmp_lt_i32 s74, 12
	s_cselect_b64 s[0:1], -1, 0
	s_cmp_gt_i32 s75, 11
	s_cselect_b64 s[2:3], -1, 0
	s_and_b64 s[0:1], s[0:1], s[2:3]
	s_andn2_b64 vcc, exec, s[0:1]
	s_cbranch_vccnz .LBB0_1405
	s_mov_b64 s[2:3], s[72:73]
	s_load_dwordx2 s[0:1], s[2:3], 0x30
	s_load_dwordx2 s[10:11], s[2:3], 0xa0
	s_add_i32 s2, 0, 0x2080c
	s_waitcnt vmcnt(0)
	v_mov_b32_e32 v8, v220
	v_mov_b32_e32 v0, s2
	ds_read_b32 v0, v0
	s_waitcnt lgkmcnt(0)
	v_ashrrev_i32_e32 v1, 6, v8
	s_lshl_b32 s2, s96, 3
	v_and_b32_e32 v146, 63, v8
	v_lshlrev_b32_e32 v128, 2, v146
	v_readfirstlane_b32 s33, v0
	v_lshl_add_u32 v147, v0, 3, v1
	v_and_b32_e32 v0, 1, v0
	v_cmp_eq_u32_e64 s[4:5], 0, v0
	v_add_u32_e32 v149, s2, v147
	s_and_b64 vcc, exec, s[4:5]
	v_add_u32_e32 v148, s2, v149
	s_cbranch_vccnz .LBB0_1297
	s_movk_i32 s16, 0x1600
	v_cmp_gt_i32_e64 s[6:7], s16, v149
	s_mov_b32 s17, 0x2e8ba2e9
	s_add_u32 s2, s0, 0x1600000
	v_cndmask_b32_e64 v0, v147, v149, s[6:7]
	v_mul_hi_i32 v1, v0, s17
	v_lshrrev_b32_e32 v2, 31, v1
	v_ashrrev_i32_e32 v1, 6, v1
	v_add_u32_e32 v6, v1, v2
	v_mul_i32_i24_e32 v1, 0xfffffea0, v6
	v_add_lshl_u32 v0, v1, v0, 3
	v_ashrrev_i32_e32 v1, 31, v0
	s_addc_u32 s3, s1, 0
	v_lshlrev_b64 v[2:3], 12, v[0:1]
	v_lshl_add_u64 v[4:5], s[2:3], 0, v[2:3]
	v_lshlrev_b32_e32 v2, 6, v6
	v_ashrrev_i32_e32 v3, 31, v2
	v_mov_b32_e32 v129, 0
	v_lshl_add_u64 v[4:5], v[2:3], 2, v[4:5]
	v_lshl_add_u64 v[24:25], v[4:5], 0, v[128:129]
	s_movk_i32 s18, 0x2000
	v_add_co_u32_e32 v26, vcc, s18, v24
	s_movk_i32 s19, 0x4000
	s_nop 0
	v_addc_co_u32_e32 v27, vcc, 0, v25, vcc
	v_add_co_u32_e32 v16, vcc, s19, v24
	s_movk_i32 s20, 0x6000
	s_nop 0
	v_addc_co_u32_e32 v17, vcc, 0, v25, vcc
	v_add_co_u32_e32 v18, vcc, s20, v24
	s_movk_i32 s8, 0x7000
	s_nop 0
	v_addc_co_u32_e32 v19, vcc, 0, v25, vcc
	v_add_co_u32_e32 v28, vcc, s8, v24
	v_cmp_gt_i32_e64 s[8:9], s16, v148
	s_nop 0
	v_addc_co_u32_e32 v29, vcc, 0, v25, vcc
	v_cndmask_b32_e64 v3, v147, v148, s[8:9]
	v_mul_hi_i32 v4, v3, s17
	v_lshrrev_b32_e32 v5, 31, v4
	v_ashrrev_i32_e32 v4, 6, v4
	v_add_u32_e32 v9, v4, v5
	v_mul_i32_i24_e32 v4, 0xfffffea0, v9
	v_add_lshl_u32 v4, v4, v3, 3
	v_ashrrev_i32_e32 v5, 31, v4
	v_lshlrev_b64 v[6:7], 12, v[4:5]
	v_lshl_add_u64 v[10:11], s[2:3], 0, v[6:7]
	v_lshlrev_b32_e32 v6, 6, v9
	v_ashrrev_i32_e32 v7, 31, v6
	v_lshl_add_u64 v[10:11], v[6:7], 2, v[10:11]
	v_lshl_add_u64 v[30:31], v[10:11], 0, v[128:129]
	v_add_co_u32_e32 v20, vcc, s18, v30
	s_movk_i32 s12, 0x5000
	s_nop 0
	v_addc_co_u32_e32 v21, vcc, 0, v31, vcc
	v_add_co_u32_e32 v22, vcc, s19, v30
	s_nop 1
	v_addc_co_u32_e32 v23, vcc, 0, v31, vcc
	v_add_co_u32_e32 v32, vcc, s12, v30
	global_load_dword v15, v[16:17], off offset:-4096 nt
	global_load_dword v12, v[16:17], off nt
	global_load_dword v13, v[18:19], off offset:-4096 nt
	global_load_dword v11, v[18:19], off nt
	global_load_dword v9, v[20:21], off offset:-4096 nt
	global_load_dword v3, v[20:21], off nt
	global_load_dword v10, v[22:23], off offset:-4096 nt
	global_load_dword v7, v[22:23], off nt
	v_addc_co_u32_e32 v33, vcc, 0, v31, vcc
	v_add_co_u32_e32 v34, vcc, 0x6000, v30
	s_add_u32 s12, s10, 0xfb00000
	s_nop 0
	v_addc_co_u32_e32 v35, vcc, 0, v31, vcc
	v_add_co_u32_e32 v36, vcc, 0x7000, v30
	s_addc_u32 s13, s11, 0
	s_nop 0
	v_addc_co_u32_e32 v37, vcc, 0, v31, vcc
	global_load_dword v21, v[24:25], off nt
	global_load_dword v22, v[26:27], off offset:-4096 nt
	global_load_dword v20, v[26:27], off nt
	global_load_dword v19, v[28:29], off nt
	global_load_dword v18, v[30:31], off nt
	global_load_dword v16, v[32:33], off nt
	global_load_dword v14, v[34:35], off nt
	global_load_dword v17, v[36:37], off nt
	v_cmp_gt_i32_e32 vcc, s16, v147
	s_and_saveexec_b64 s[14:15], vcc
	s_cbranch_execnz .LBB0_1327
	s_or_b64 exec, exec, s[14:15]
	s_and_saveexec_b64 s[2:3], s[6:7]
	s_cbranch_execnz .LBB0_1328

; __device__ __forceinline__ void conv_addr(const ConvJob& j, int wi, int lane, const float*& src, int& stride, bf16_t*& dst, const float*& kg) {
;     ...
;     else { const int nb = wi / 352, k0 = (wi - nb * 352) * 8;
;         src = j.s0 + (size_t)k0 * D + nb * 64 + lane; stride = D; dst = j.dst + (size_t)(nb * 64 + lane) * FF + k0; kg = nullptr; }
; template <int NMAX>
; __device__ __forceinline__ void conv_block(const ConvJob& j, int total, int gw, int NW, int lane) {
;     if (j.kind == 0) return;
;     float v[NMAX][8]; bf16_t* d[NMAX]; const float* kg[NMAX];
; #pragma unroll
;     for (int q = 0; q < NMAX; ++q) { const int wi = gw + q * NW; const float* src; int st;
;         conv_addr(j, wi < total ? wi : gw, lane, src, st, d[q], kg[q]); conv_load(src, st, v[q]); }
.LBB0_1311:
	s_movk_i32 s12, 0x1600
	v_cmp_gt_i32_e64 s[4:5], s12, v149
	s_mov_b32 s13, 0x2e8ba2e9
	s_add_u32 s0, s0, 0x1600000
	v_cndmask_b32_e64 v0, v147, v149, s[4:5]
	v_mul_hi_i32 v1, v0, s13
	v_lshrrev_b32_e32 v2, 31, v1
	v_ashrrev_i32_e32 v1, 6, v1
	v_add_u32_e32 v6, v1, v2
	v_mul_i32_i24_e32 v1, 0xfffffea0, v6
	v_add_lshl_u32 v0, v1, v0, 3
	v_ashrrev_i32_e32 v1, 31, v0
	s_addc_u32 s1, s1, 0
	v_lshlrev_b64 v[2:3], 12, v[0:1]
	v_lshl_add_u64 v[4:5], s[0:1], 0, v[2:3]
	v_lshlrev_b32_e32 v2, 6, v6
	v_ashrrev_i32_e32 v3, 31, v2
	v_cmp_gt_i32_e64 s[6:7], s12, v148
	v_mov_b32_e32 v129, 0
	v_lshl_add_u64 v[4:5], v[2:3], 2, v[4:5]
	v_cndmask_b32_e64 v3, v147, v148, s[6:7]
	v_lshl_add_u64 v[22:23], v[4:5], 0, v[128:129]
	v_mul_hi_i32 v4, v3, s13
	v_lshrrev_b32_e32 v5, 31, v4
	v_ashrrev_i32_e32 v4, 6, v4
	s_movk_i32 s14, 0x2000
	v_add_u32_e32 v10, v4, v5
	v_add_co_u32_e32 v24, vcc, s14, v22
	v_mul_i32_i24_e32 v4, 0xfffffea0, v10
	s_nop 0
	v_addc_co_u32_e32 v25, vcc, 0, v23, vcc
	s_movk_i32 s15, 0x4000
	v_add_lshl_u32 v4, v4, v3, 3
	v_add_co_u32_e32 v16, vcc, s15, v22
	v_ashrrev_i32_e32 v5, 31, v4
	s_nop 0
	v_addc_co_u32_e32 v17, vcc, 0, v23, vcc
	s_movk_i32 s16, 0x6000
	v_lshlrev_b64 v[6:7], 12, v[4:5]
	v_add_co_u32_e32 v18, vcc, s16, v22
	v_lshl_add_u64 v[8:9], s[0:1], 0, v[6:7]
	v_lshlrev_b32_e32 v6, 6, v10
	v_addc_co_u32_e32 v19, vcc, 0, v23, vcc
	s_movk_i32 s3, 0x7000
	v_ashrrev_i32_e32 v7, 31, v6
	v_add_co_u32_e32 v26, vcc, s3, v22
	v_lshl_add_u64 v[8:9], v[6:7], 2, v[8:9]
	s_nop 0
	v_addc_co_u32_e32 v27, vcc, 0, v23, vcc
	v_lshl_add_u64 v[28:29], v[8:9], 0, v[128:129]
	v_add_co_u32_e32 v20, vcc, s14, v28
	s_movk_i32 s2, 0x5000
	s_nop 0
	v_addc_co_u32_e32 v21, vcc, 0, v29, vcc
	v_add_co_u32_e32 v30, vcc, s15, v28
	s_nop 1
	v_addc_co_u32_e32 v31, vcc, 0, v29, vcc
	global_load_dword v14, v[16:17], off offset:-4096 nt
	global_load_dword v11, v[16:17], off nt
	global_load_dword v12, v[18:19], off offset:-4096 nt
	global_load_dword v10, v[18:19], off nt
	global_load_dword v8, v[20:21], off offset:-4096 nt
	global_load_dword v3, v[20:21], off nt
	global_load_dword v9, v[30:31], off offset:-4096 nt
	global_load_dword v7, v[30:31], off nt
	v_add_co_u32_e32 v30, vcc, s2, v28
	s_add_u32 s2, s10, 0xfb00000
	s_nop 0
	v_addc_co_u32_e32 v31, vcc, 0, v29, vcc
	v_add_co_u32_e32 v32, vcc, 0x6000, v28
	s_addc_u32 s3, s11, 0
	s_nop 0
	v_addc_co_u32_e32 v33, vcc, 0, v29, vcc
	v_add_co_u32_e32 v34, vcc, 0x7000, v28
	s_nop 1
	v_addc_co_u32_e32 v35, vcc, 0, v29, vcc
	global_load_dword v20, v[22:23], off nt
	global_load_dword v21, v[24:25], off offset:-4096 nt
	global_load_dword v19, v[24:25], off nt
	global_load_dword v18, v[26:27], off nt
	global_load_dword v17, v[28:29], off nt
	global_load_dword v15, v[30:31], off nt
	global_load_dword v13, v[32:33], off nt
	global_load_dword v16, v[34:35], off nt
	v_cmp_gt_i32_e32 vcc, s12, v147
	s_and_saveexec_b64 s[8:9], vcc
	s_cbranch_execnz .LBB0_1329
	s_or_b64 exec, exec, s[8:9]
	s_and_saveexec_b64 s[0:1], s[4:5]
	s_cbranch_execnz .LBB0_1330

; __device__ __forceinline__ void conv_addr(const ConvJob& j, int wi, int lane, const float*& src, int& stride, bf16_t*& dst, const float*& kg) {
;     if (j.kind == 1) { const int rb = wi >> 7, k0 = (wi & 127) * 8, pn = rb >> 2, bj = (rb >> 1) & 1;
;         src = j.s0 + (ptrdiff_t)bj * j.d10 + (size_t)k0 * FF + pn * 128 + (rb & 1) * 64 + lane; stride = FF; dst = j.dst + (size_t)(rb * 64 + lane) * D + k0; kg = j.gain + k0; }
; template <int NMAX>
; __device__ __forceinline__ void conv_block(const ConvJob& j, int total, int gw, int NW, int lane) {
;     if (j.kind == 0) return;
;     float v[NMAX][8]; bf16_t* d[NMAX]; const float* kg[NMAX];
; #pragma unroll
;     for (int q = 0; q < NMAX; ++q) { const int wi = gw + q * NW; const float* src; int st;
;         conv_addr(j, wi < total ? wi : gw, lane, src, st, d[q], kg[q]); conv_load(src, st, v[q]); }
.LBB0_1405:
	s_cmp_lt_i32 s74, 13
	s_cselect_b64 s[0:1], -1, 0
	s_cmp_gt_i32 s75, 12
	s_cselect_b64 s[2:3], -1, 0
	s_and_b64 s[0:1], s[0:1], s[2:3]
	s_andn2_b64 vcc, exec, s[0:1]
	s_cbranch_vccnz .LBB0_1554
	s_mov_b64 s[0:1], s[72:73]
	s_load_dwordx2 s[22:23], s[0:1], 0x10
	s_load_dwordx4 s[16:19], s[0:1], 0x20
	s_load_dwordx2 s[20:21], s[0:1], 0xa0
	s_add_i32 s0, 0, 0x2080c
	v_mov_b32_e32 v0, v220
	s_waitcnt lgkmcnt(0)
	v_mov_b32_e32 v1, s0
	ds_read_b32 v1, v1
	v_and_b32_e32 v184, 63, v0
	v_ashrrev_i32_e32 v0, 6, v0
	s_lshl_b32 s33, s96, 3
	v_lshlrev_b32_e32 v152, 2, v184
	s_waitcnt lgkmcnt(0)
	v_lshl_add_u32 v185, v1, 3, v0
	v_and_b32_e32 v0, 1, v1
	v_cmp_eq_u32_e64 s[4:5], 0, v0
	v_add_u32_e32 v187, s33, v185
	v_readfirstlane_b32 s38, v1
	s_and_b64 vcc, exec, s[4:5]
	v_add_u32_e32 v186, s33, v187
	s_cbranch_vccnz .LBB0_1415
	s_add_u32 s0, s16, 0x2100000
	s_addc_u32 s1, s17, 0
	s_movk_i32 s35, 0x2c00
	s_sub_u32 s2, s18, s16
	v_cmp_gt_i32_e64 s[6:7], s35, v187
	s_subb_u32 s3, s19, s17
	s_ashr_i64 s[2:3], s[2:3], 2
	v_cndmask_b32_e64 v1, v185, v187, s[6:7]
	v_bfe_u32 v2, v1, 8, 1
	v_lshlrev_b32_e32 v0, 3, v1
	s_waitcnt vmcnt(0)
	v_mul_lo_u32 v3, s3, v2
	v_mul_lo_u32 v2, s2, v2
	v_ashrrev_i32_e32 v4, 2, v1
	v_and_b32_e32 v0, 0x3f8, v0
	v_lshl_add_u64 v[2:3], v[2:3], 2, s[0:1]
	v_and_b32_e32 v4, 0xffffff80, v4
	v_mad_u64_u32 v[2:3], s[8:9], v0, s35, v[2:3]
	v_ashrrev_i32_e32 v5, 31, v4
	v_ashrrev_i32_e32 v1, 1, v1
	v_mov_b32_e32 v153, 0
	v_lshl_add_u64 v[2:3], v[4:5], 2, v[2:3]
	v_lshlrev_b32_e32 v4, 2, v1
	v_and_b32_e32 v4, 0x100, v4
	v_mov_b32_e32 v5, v153
	v_lshl_add_u64 v[2:3], v[2:3], 0, v[4:5]
	v_lshl_add_u64 v[2:3], v[2:3], 0, v[152:153]
	s_movk_i32 s30, 0x2000
	v_add_co_u32_e32 v14, vcc, s30, v2
	s_movk_i32 s34, 0x5000
	s_nop 0
	v_addc_co_u32_e32 v15, vcc, 0, v3, vcc
	v_add_co_u32_e32 v16, vcc, s34, v2
	s_mov_b32 s36, 0x8000
	s_nop 0
	v_addc_co_u32_e32 v17, vcc, 0, v3, vcc
	v_add_co_u32_e32 v18, vcc, s36, v2
	s_mov_b32 s37, 0xb000
	s_nop 0
	v_addc_co_u32_e32 v19, vcc, 0, v3, vcc
	v_add_co_u32_e32 v20, vcc, s37, v2
	s_mov_b32 s39, 0xd000
	s_nop 0
	v_addc_co_u32_e32 v21, vcc, 0, v3, vcc
	v_add_co_u32_e32 v22, vcc, s39, v2
	s_mov_b32 s40, 0x10000
	s_nop 0
	v_addc_co_u32_e32 v23, vcc, 0, v3, vcc
	v_add_co_u32_e32 v24, vcc, s40, v2
	s_mov_b32 s31, 0x13000
	s_nop 0
	v_addc_co_u32_e32 v25, vcc, 0, v3, vcc
	v_add_co_u32_e32 v26, vcc, s31, v2
	v_cmp_gt_i32_e64 s[8:9], s35, v186
	s_nop 0
	v_addc_co_u32_e32 v27, vcc, 0, v3, vcc
	global_load_dword v11, v[2:3], off nt
	global_load_dword v12, v[14:15], off offset:3072 nt
	global_load_dword v8, v[16:17], off offset:2048 nt
	global_load_dword v9, v[18:19], off offset:1024 nt
	global_load_dword v5, v[20:21], off nt
	global_load_dword v6, v[22:23], off offset:3072 nt
	global_load_dword v4, v[24:25], off offset:2048 nt
	global_load_dword v10, v[26:27], off offset:1024 nt
	v_cndmask_b32_e64 v3, v185, v186, s[8:9]
	v_bfe_u32 v7, v3, 8, 1
	v_lshlrev_b32_e32 v2, 3, v3
	v_mul_lo_u32 v15, s3, v7
	v_mul_lo_u32 v14, s2, v7
	v_ashrrev_i32_e32 v7, 2, v3
	v_and_b32_e32 v2, 0x3f8, v2
	v_lshl_add_u64 v[14:15], v[14:15], 2, s[0:1]
	v_and_b32_e32 v16, 0xffffff80, v7
	v_ashrrev_i32_e32 v3, 1, v3
	v_mad_u64_u32 v[14:15], s[10:11], v2, s35, v[14:15]
	v_ashrrev_i32_e32 v17, 31, v16
	v_lshlrev_b32_e32 v7, 2, v3
	v_lshl_add_u64 v[14:15], v[16:17], 2, v[14:15]
	v_and_b32_e32 v16, 0x100, v7
	v_mov_b32_e32 v17, v153
	v_lshl_add_u64 v[14:15], v[14:15], 0, v[16:17]
	v_lshl_add_u64 v[24:25], v[14:15], 0, v[152:153]
	v_add_co_u32_e32 v26, vcc, s30, v24
	v_add_u32_e32 v20, s33, v186
	s_nop 0
	v_addc_co_u32_e32 v27, vcc, 0, v25, vcc
	v_add_co_u32_e32 v28, vcc, s34, v24
	v_cmp_gt_i32_e64 s[10:11], s35, v20
	s_nop 0
	v_addc_co_u32_e32 v29, vcc, 0, v25, vcc
	v_add_co_u32_e32 v30, vcc, s36, v24
	v_cndmask_b32_e64 v13, v185, v20, s[10:11]
	s_nop 0
	v_addc_co_u32_e32 v31, vcc, 0, v25, vcc
	v_add_co_u32_e32 v32, vcc, s37, v24
	v_bfe_u32 v23, v13, 8, 1
	s_nop 0
	v_addc_co_u32_e32 v33, vcc, 0, v25, vcc
	v_add_co_u32_e32 v34, vcc, s39, v24
	v_lshlrev_b32_e32 v7, 3, v13
	s_nop 0
	v_addc_co_u32_e32 v35, vcc, 0, v25, vcc
	v_add_co_u32_e32 v36, vcc, s40, v24
	v_and_b32_e32 v7, 0x3f8, v7
	s_nop 0
	v_addc_co_u32_e32 v37, vcc, 0, v25, vcc
	v_add_co_u32_e32 v38, vcc, s31, v24
	s_add_u32 s26, s22, 0x5000
	s_nop 0
	v_addc_co_u32_e32 v39, vcc, 0, v25, vcc
	global_load_dword v21, v[24:25], off nt
	global_load_dword v22, v[26:27], off offset:3072 nt
	global_load_dword v17, v[28:29], off offset:2048 nt
	global_load_dword v18, v[30:31], off offset:1024 nt
	global_load_dword v15, v[32:33], off nt
	global_load_dword v16, v[34:35], off offset:3072 nt
	global_load_dword v14, v[36:37], off offset:2048 nt
	global_load_dword v19, v[38:39], off offset:1024 nt
	v_mul_lo_u32 v25, s3, v23
	v_mul_lo_u32 v24, s2, v23
	v_ashrrev_i32_e32 v23, 2, v13
	v_lshl_add_u64 v[24:25], v[24:25], 2, s[0:1]
	v_and_b32_e32 v26, 0xffffff80, v23
	v_ashrrev_i32_e32 v13, 1, v13
	v_mad_u64_u32 v[24:25], s[12:13], v7, s35, v[24:25]
; __device__ __forceinline__ void conv_addr(const ConvJob& j, int wi, int lane, const float*& src, int& stride, bf16_t*& dst, const float*& kg) {
;     if (j.kind == 1) { const int rb = wi >> 7, k0 = (wi & 127) * 8, pn = rb >> 2, bj = (rb >> 1) & 1;
;         src = j.s0 + (ptrdiff_t)bj * j.d10 + (size_t)k0 * FF + pn * 128 + (rb & 1) * 64 + lane; stride = FF; dst = j.dst + (size_t)(rb * 64 + lane) * D + k0; kg = j.gain + k0; }
; template <int NMAX>
; __device__ __forceinline__ void conv_block(const ConvJob& j, int total, int gw, int NW, int lane) {
;     if (j.kind == 0) return;
;     float v[NMAX][8]; bf16_t* d[NMAX]; const float* kg[NMAX];
; #pragma unroll
;     for (int q = 0; q < NMAX; ++q) { const int wi = gw + q * NW; const float* src; int st;
;         conv_addr(j, wi < total ? wi : gw, lane, src, st, d[q], kg[q]); conv_load(src, st, v[q]); }
	v_ashrrev_i32_e32 v27, 31, v26
	v_lshlrev_b32_e32 v23, 2, v13
	v_lshl_add_u64 v[24:25], v[26:27], 2, v[24:25]
	v_and_b32_e32 v26, 0x100, v23
	v_mov_b32_e32 v27, v153
	v_lshl_add_u64 v[24:25], v[24:25], 0, v[26:27]
	v_lshl_add_u64 v[34:35], v[24:25], 0, v[152:153]
	v_add_co_u32_e32 v36, vcc, s30, v34
	v_add_u32_e32 v27, s33, v20
	s_nop 0
	v_addc_co_u32_e32 v37, vcc, 0, v35, vcc
	v_add_co_u32_e32 v38, vcc, s34, v34
	v_cmp_gt_i32_e64 s[12:13], s35, v27
	s_nop 0
	v_addc_co_u32_e32 v39, vcc, 0, v35, vcc
	v_add_co_u32_e32 v40, vcc, s36, v34
	v_cndmask_b32_e64 v23, v185, v27, s[12:13]
	s_nop 0
	v_addc_co_u32_e32 v41, vcc, 0, v35, vcc
	v_add_co_u32_e32 v42, vcc, s37, v34
	v_bfe_u32 v33, v23, 8, 1
	s_nop 0
	v_addc_co_u32_e32 v43, vcc, 0, v35, vcc
	v_add_co_u32_e32 v44, vcc, s39, v34
	v_lshlrev_b32_e32 v20, 3, v23
	s_nop 0
	v_addc_co_u32_e32 v45, vcc, 0, v35, vcc
	v_add_co_u32_e32 v46, vcc, s40, v34
	v_and_b32_e32 v20, 0x3f8, v20
	s_nop 0
	v_addc_co_u32_e32 v47, vcc, 0, v35, vcc
	v_add_co_u32_e32 v48, vcc, s31, v34
	v_add_u32_e32 v27, s33, v27
	s_nop 0
	v_addc_co_u32_e32 v49, vcc, 0, v35, vcc
	global_load_dword v31, v[34:35], off nt
	global_load_dword v32, v[36:37], off offset:3072 nt
	global_load_dword v28, v[38:39], off offset:2048 nt
	global_load_dword v29, v[40:41], off offset:1024 nt
	global_load_dword v25, v[42:43], off nt
	global_load_dword v26, v[44:45], off offset:3072 nt
	global_load_dword v24, v[46:47], off offset:2048 nt
	global_load_dword v30, v[48:49], off offset:1024 nt
	v_mul_lo_u32 v35, s3, v33
	v_mul_lo_u32 v34, s2, v33
	v_ashrrev_i32_e32 v33, 2, v23
	v_lshl_add_u64 v[34:35], v[34:35], 2, s[0:1]
	v_and_b32_e32 v36, 0xffffff80, v33
	v_ashrrev_i32_e32 v23, 1, v23
	v_mad_u64_u32 v[34:35], s[14:15], v20, s35, v[34:35]
	v_ashrrev_i32_e32 v37, 31, v36
	v_lshlrev_b32_e32 v33, 2, v23
	v_lshl_add_u64 v[34:35], v[36:37], 2, v[34:35]
	v_and_b32_e32 v36, 0x100, v33
	v_mov_b32_e32 v37, v153
	v_lshl_add_u64 v[34:35], v[34:35], 0, v[36:37]
	v_lshl_add_u64 v[42:43], v[34:35], 0, v[152:153]
	v_add_co_u32_e32 v44, vcc, s30, v42
	v_cmp_gt_i32_e64 s[14:15], s35, v27
	s_nop 0
	v_addc_co_u32_e32 v45, vcc, 0, v43, vcc
	v_add_co_u32_e32 v46, vcc, s34, v42
	v_cndmask_b32_e64 v33, v185, v27, s[14:15]
	s_nop 0
	v_addc_co_u32_e32 v47, vcc, 0, v43, vcc
	v_add_co_u32_e32 v48, vcc, s36, v42
	v_lshlrev_b32_e32 v27, 3, v33
	s_nop 0
	v_addc_co_u32_e32 v49, vcc, 0, v43, vcc
	v_add_co_u32_e32 v50, vcc, s37, v42
	v_and_b32_e32 v27, 0x3f8, v27
	s_nop 0
	v_addc_co_u32_e32 v51, vcc, 0, v43, vcc
	v_add_co_u32_e32 v52, vcc, s39, v42
	s_addc_u32 s27, s23, 0
	s_nop 0
	v_addc_co_u32_e32 v53, vcc, 0, v43, vcc
	v_add_co_u32_e32 v54, vcc, s40, v42
	s_nop 1
	v_addc_co_u32_e32 v55, vcc, 0, v43, vcc
	v_add_co_u32_e32 v56, vcc, s31, v42
	s_nop 1
	v_addc_co_u32_e32 v57, vcc, 0, v43, vcc
	global_load_dword v40, v[42:43], off nt
	global_load_dword v41, v[44:45], off offset:3072 nt
	global_load_dword v37, v[46:47], off offset:2048 nt
	global_load_dword v38, v[48:49], off offset:1024 nt
	global_load_dword v35, v[50:51], off nt
	global_load_dword v36, v[52:53], off offset:3072 nt
	global_load_dword v34, v[54:55], off offset:2048 nt
	global_load_dword v39, v[56:57], off offset:1024 nt
	v_bfe_u32 v42, v33, 8, 1
	v_mul_lo_u32 v43, s3, v42
	v_mul_lo_u32 v42, s2, v42
	v_ashrrev_i32_e32 v44, 2, v33
	v_lshl_add_u64 v[42:43], v[42:43], 2, s[0:1]
	v_and_b32_e32 v44, 0xffffff80, v44
	v_mad_u64_u32 v[42:43], s[24:25], v27, s35, v[42:43]
	v_ashrrev_i32_e32 v45, 31, v44
	v_ashrrev_i32_e32 v33, 1, v33
	v_lshl_add_u64 v[42:43], v[44:45], 2, v[42:43]
	v_lshlrev_b32_e32 v44, 2, v33
	v_and_b32_e32 v44, 0x100, v44
	v_mov_b32_e32 v45, v153
	v_lshl_add_u64 v[42:43], v[42:43], 0, v[44:45]
	v_lshl_add_u64 v[50:51], v[42:43], 0, v[152:153]
	v_add_co_u32_e32 v52, vcc, s30, v50
	s_add_u32 s24, s20, 0xf000000
	s_nop 0
	v_addc_co_u32_e32 v53, vcc, 0, v51, vcc
	v_add_co_u32_e32 v54, vcc, s34, v50
	s_addc_u32 s25, s21, 0
	s_nop 0
	v_addc_co_u32_e32 v55, vcc, 0, v51, vcc
	v_add_co_u32_e32 v56, vcc, s36, v50
	s_nop 1
	v_addc_co_u32_e32 v57, vcc, 0, v51, vcc
	v_add_co_u32_e32 v58, vcc, s37, v50
	s_nop 1
	v_addc_co_u32_e32 v59, vcc, 0, v51, vcc
	v_add_co_u32_e32 v60, vcc, s39, v50
	s_nop 1
	v_addc_co_u32_e32 v61, vcc, 0, v51, vcc
	v_add_co_u32_e32 v62, vcc, 0x10000, v50
	s_nop 1
	v_addc_co_u32_e32 v63, vcc, 0, v51, vcc
	v_add_co_u32_e32 v64, vcc, 0x13000, v50
	s_nop 1
	v_addc_co_u32_e32 v65, vcc, 0, v51, vcc
	global_load_dword v48, v[50:51], off nt
	global_load_dword v49, v[52:53], off offset:3072 nt
	global_load_dword v45, v[54:55], off offset:2048 nt
	global_load_dword v46, v[56:57], off offset:1024 nt
	global_load_dword v43, v[58:59], off nt
	global_load_dword v44, v[60:61], off offset:3072 nt
	global_load_dword v42, v[62:63], off offset:2048 nt
	global_load_dword v47, v[64:65], off offset:1024 nt
	v_cmp_gt_i32_e32 vcc, s35, v185
	s_and_saveexec_b64 s[28:29], vcc
	s_cbranch_execnz .LBB0_1470
	s_or_b64 exec, exec, s[28:29]
	s_and_saveexec_b64 s[0:1], s[6:7]
	s_cbranch_execnz .LBB0_1471

; __device__ __forceinline__ void conv_addr(const ConvJob& j, int wi, int lane, const float*& src, int& stride, bf16_t*& dst, const float*& kg) {
;     if (j.kind == 1) { const int rb = wi >> 7, k0 = (wi & 127) * 8, pn = rb >> 2, bj = (rb >> 1) & 1;
;         src = j.s0 + (ptrdiff_t)bj * j.d10 + (size_t)k0 * FF + pn * 128 + (rb & 1) * 64 + lane; stride = FF; dst = j.dst + (size_t)(rb * 64 + lane) * D + k0; kg = j.gain + k0; }
; template <int NMAX>
; __device__ __forceinline__ void conv_block(const ConvJob& j, int total, int gw, int NW, int lane) {
;     if (j.kind == 0) return;
;     float v[NMAX][8]; bf16_t* d[NMAX]; const float* kg[NMAX];
; #pragma unroll
;     for (int q = 0; q < NMAX; ++q) { const int wi = gw + q * NW; const float* src; int st;
;         conv_addr(j, wi < total ? wi : gw, lane, src, st, d[q], kg[q]); conv_load(src, st, v[q]); }
.LBB0_1451:
	s_add_u32 s0, s16, 0x2100000
	s_addc_u32 s1, s17, 0
	s_movk_i32 s27, 0x2c00
	s_sub_u32 s2, s18, s16
	v_cmp_gt_i32_e64 s[4:5], s27, v187
	s_subb_u32 s3, s19, s17
	s_ashr_i64 s[2:3], s[2:3], 2
	s_waitcnt lgkmcnt(0)
	v_cndmask_b32_e64 v1, v185, v187, s[4:5]
	v_bfe_u32 v2, v1, 8, 1
	v_lshlrev_b32_e32 v0, 3, v1
	v_mul_lo_u32 v3, s3, v2
	v_mul_lo_u32 v2, s2, v2
	v_ashrrev_i32_e32 v4, 2, v1
	v_and_b32_e32 v0, 0x3f8, v0
	v_lshl_add_u64 v[2:3], v[2:3], 2, s[0:1]
	v_and_b32_e32 v4, 0xffffff80, v4
	v_mad_u64_u32 v[2:3], s[6:7], v0, s27, v[2:3]
	v_ashrrev_i32_e32 v5, 31, v4
	v_ashrrev_i32_e32 v1, 1, v1
	v_mov_b32_e32 v153, 0
	v_lshl_add_u64 v[2:3], v[4:5], 2, v[2:3]
	v_lshlrev_b32_e32 v4, 2, v1
	v_and_b32_e32 v4, 0x100, v4
	v_mov_b32_e32 v5, v153
	v_lshl_add_u64 v[2:3], v[2:3], 0, v[4:5]
	v_lshl_add_u64 v[2:3], v[2:3], 0, v[152:153]
	s_movk_i32 s24, 0x2000
	v_add_co_u32_e32 v14, vcc, s24, v2
	s_movk_i32 s26, 0x5000
	s_nop 0
	v_addc_co_u32_e32 v15, vcc, 0, v3, vcc
	v_add_co_u32_e32 v16, vcc, s26, v2
	s_mov_b32 s28, 0x8000
	s_nop 0
	v_addc_co_u32_e32 v17, vcc, 0, v3, vcc
	v_add_co_u32_e32 v18, vcc, s28, v2
	s_mov_b32 s29, 0xb000
	s_nop 0
	v_addc_co_u32_e32 v19, vcc, 0, v3, vcc
	v_add_co_u32_e32 v20, vcc, s29, v2
	s_mov_b32 s30, 0xd000
	s_nop 0
	v_addc_co_u32_e32 v21, vcc, 0, v3, vcc
	v_add_co_u32_e32 v22, vcc, s30, v2
	s_mov_b32 s31, 0x10000
	s_nop 0
	v_addc_co_u32_e32 v23, vcc, 0, v3, vcc
	v_add_co_u32_e32 v24, vcc, s31, v2
	s_mov_b32 s25, 0x13000
	s_nop 0
	v_addc_co_u32_e32 v25, vcc, 0, v3, vcc
	v_add_co_u32_e32 v26, vcc, s25, v2
	v_cmp_gt_i32_e64 s[6:7], s27, v186
	s_nop 0
	v_addc_co_u32_e32 v27, vcc, 0, v3, vcc
	global_load_dword v11, v[2:3], off nt
	global_load_dword v12, v[14:15], off offset:3072 nt
	global_load_dword v8, v[16:17], off offset:2048 nt
	global_load_dword v9, v[18:19], off offset:1024 nt
	global_load_dword v5, v[20:21], off nt
	global_load_dword v6, v[22:23], off offset:3072 nt
	global_load_dword v4, v[24:25], off offset:2048 nt
	global_load_dword v10, v[26:27], off offset:1024 nt
	v_cndmask_b32_e64 v3, v185, v186, s[6:7]
	v_bfe_u32 v7, v3, 8, 1
	v_lshlrev_b32_e32 v2, 3, v3
	v_mul_lo_u32 v15, s3, v7
	v_mul_lo_u32 v14, s2, v7
	v_ashrrev_i32_e32 v7, 2, v3
	v_and_b32_e32 v2, 0x3f8, v2
	v_lshl_add_u64 v[14:15], v[14:15], 2, s[0:1]
	v_and_b32_e32 v16, 0xffffff80, v7
	v_ashrrev_i32_e32 v3, 1, v3
	v_mad_u64_u32 v[14:15], s[8:9], v2, s27, v[14:15]
	v_ashrrev_i32_e32 v17, 31, v16
	v_lshlrev_b32_e32 v7, 2, v3
	v_lshl_add_u64 v[14:15], v[16:17], 2, v[14:15]
	v_and_b32_e32 v16, 0x100, v7
	v_mov_b32_e32 v17, v153
	v_lshl_add_u64 v[14:15], v[14:15], 0, v[16:17]
	v_lshl_add_u64 v[24:25], v[14:15], 0, v[152:153]
	v_add_co_u32_e32 v26, vcc, s24, v24
	v_add_u32_e32 v20, s33, v186
	s_nop 0
	v_addc_co_u32_e32 v27, vcc, 0, v25, vcc
	v_add_co_u32_e32 v28, vcc, s26, v24
	v_cmp_gt_i32_e64 s[8:9], s27, v20
	s_nop 0
	v_addc_co_u32_e32 v29, vcc, 0, v25, vcc
	v_add_co_u32_e32 v30, vcc, s28, v24
	v_cndmask_b32_e64 v13, v185, v20, s[8:9]
	s_nop 0
	v_addc_co_u32_e32 v31, vcc, 0, v25, vcc
	v_add_co_u32_e32 v32, vcc, s29, v24
	v_bfe_u32 v23, v13, 8, 1
	s_nop 0
	v_addc_co_u32_e32 v33, vcc, 0, v25, vcc
	v_add_co_u32_e32 v34, vcc, s30, v24
	v_lshlrev_b32_e32 v7, 3, v13
	s_nop 0
	v_addc_co_u32_e32 v35, vcc, 0, v25, vcc
	v_add_co_u32_e32 v36, vcc, s31, v24
	v_and_b32_e32 v7, 0x3f8, v7
	s_nop 0
	v_addc_co_u32_e32 v37, vcc, 0, v25, vcc
	v_add_co_u32_e32 v38, vcc, s25, v24
	s_add_u32 s16, s22, 0x5000
	s_nop 0
	v_addc_co_u32_e32 v39, vcc, 0, v25, vcc
	global_load_dword v21, v[24:25], off nt
	global_load_dword v22, v[26:27], off offset:3072 nt
	global_load_dword v17, v[28:29], off offset:2048 nt
	global_load_dword v18, v[30:31], off offset:1024 nt
	global_load_dword v15, v[32:33], off nt
	global_load_dword v16, v[34:35], off offset:3072 nt
	global_load_dword v14, v[36:37], off offset:2048 nt
	global_load_dword v19, v[38:39], off offset:1024 nt
	v_mul_lo_u32 v25, s3, v23
	v_mul_lo_u32 v24, s2, v23
	v_ashrrev_i32_e32 v23, 2, v13
	v_lshl_add_u64 v[24:25], v[24:25], 2, s[0:1]
	v_and_b32_e32 v26, 0xffffff80, v23
	v_ashrrev_i32_e32 v13, 1, v13
	v_mad_u64_u32 v[24:25], s[10:11], v7, s27, v[24:25]
	v_ashrrev_i32_e32 v27, 31, v26
	v_lshlrev_b32_e32 v23, 2, v13
	v_lshl_add_u64 v[24:25], v[26:27], 2, v[24:25]
	v_and_b32_e32 v26, 0x100, v23
	v_mov_b32_e32 v27, v153
	v_lshl_add_u64 v[24:25], v[24:25], 0, v[26:27]
	v_lshl_add_u64 v[34:35], v[24:25], 0, v[152:153]
	v_add_co_u32_e32 v36, vcc, s24, v34
	v_add_u32_e32 v27, s33, v20
	s_nop 0
	v_addc_co_u32_e32 v37, vcc, 0, v35, vcc
	v_add_co_u32_e32 v38, vcc, s26, v34
; __device__ __forceinline__ void conv_addr(const ConvJob& j, int wi, int lane, const float*& src, int& stride, bf16_t*& dst, const float*& kg) {
;     if (j.kind == 1) { const int rb = wi >> 7, k0 = (wi & 127) * 8, pn = rb >> 2, bj = (rb >> 1) & 1;
;         src = j.s0 + (ptrdiff_t)bj * j.d10 + (size_t)k0 * FF + pn * 128 + (rb & 1) * 64 + lane; stride = FF; dst = j.dst + (size_t)(rb * 64 + lane) * D + k0; kg = j.gain + k0; }
; template <int NMAX>
; __device__ __forceinline__ void conv_block(const ConvJob& j, int total, int gw, int NW, int lane) {
;     if (j.kind == 0) return;
;     float v[NMAX][8]; bf16_t* d[NMAX]; const float* kg[NMAX];
; #pragma unroll
;     for (int q = 0; q < NMAX; ++q) { const int wi = gw + q * NW; const float* src; int st;
;         conv_addr(j, wi < total ? wi : gw, lane, src, st, d[q], kg[q]); conv_load(src, st, v[q]); }
	v_cmp_gt_i32_e64 s[10:11], s27, v27
	s_nop 0
	v_addc_co_u32_e32 v39, vcc, 0, v35, vcc
	v_add_co_u32_e32 v40, vcc, s28, v34
	v_cndmask_b32_e64 v23, v185, v27, s[10:11]
	s_nop 0
	v_addc_co_u32_e32 v41, vcc, 0, v35, vcc
	v_add_co_u32_e32 v42, vcc, s29, v34
	v_bfe_u32 v33, v23, 8, 1
	s_nop 0
	v_addc_co_u32_e32 v43, vcc, 0, v35, vcc
	v_add_co_u32_e32 v44, vcc, s30, v34
	v_lshlrev_b32_e32 v20, 3, v23
	s_nop 0
	v_addc_co_u32_e32 v45, vcc, 0, v35, vcc
	v_add_co_u32_e32 v46, vcc, s31, v34
	v_and_b32_e32 v20, 0x3f8, v20
	s_nop 0
	v_addc_co_u32_e32 v47, vcc, 0, v35, vcc
	v_add_co_u32_e32 v48, vcc, s25, v34
	v_add_u32_e32 v27, s33, v27
	s_nop 0
	v_addc_co_u32_e32 v49, vcc, 0, v35, vcc
	global_load_dword v31, v[34:35], off nt
	global_load_dword v32, v[36:37], off offset:3072 nt
	global_load_dword v28, v[38:39], off offset:2048 nt
	global_load_dword v29, v[40:41], off offset:1024 nt
	global_load_dword v25, v[42:43], off nt
	global_load_dword v26, v[44:45], off offset:3072 nt
	global_load_dword v24, v[46:47], off offset:2048 nt
	global_load_dword v30, v[48:49], off offset:1024 nt
	v_mul_lo_u32 v35, s3, v33
	v_mul_lo_u32 v34, s2, v33
	v_ashrrev_i32_e32 v33, 2, v23
	v_lshl_add_u64 v[34:35], v[34:35], 2, s[0:1]
	v_and_b32_e32 v36, 0xffffff80, v33
	v_ashrrev_i32_e32 v23, 1, v23
	v_mad_u64_u32 v[34:35], s[12:13], v20, s27, v[34:35]
	v_ashrrev_i32_e32 v37, 31, v36
	v_lshlrev_b32_e32 v33, 2, v23
	v_lshl_add_u64 v[34:35], v[36:37], 2, v[34:35]
	v_and_b32_e32 v36, 0x100, v33
	v_mov_b32_e32 v37, v153
	v_lshl_add_u64 v[34:35], v[34:35], 0, v[36:37]
	v_lshl_add_u64 v[42:43], v[34:35], 0, v[152:153]
	v_add_co_u32_e32 v44, vcc, s24, v42
	v_cmp_gt_i32_e64 s[12:13], s27, v27
	s_nop 0
	v_addc_co_u32_e32 v45, vcc, 0, v43, vcc
	v_add_co_u32_e32 v46, vcc, s26, v42
	v_cndmask_b32_e64 v33, v185, v27, s[12:13]
	s_nop 0
	v_addc_co_u32_e32 v47, vcc, 0, v43, vcc
	v_add_co_u32_e32 v48, vcc, s28, v42
	v_lshlrev_b32_e32 v27, 3, v33
	s_nop 0
	v_addc_co_u32_e32 v49, vcc, 0, v43, vcc
	v_add_co_u32_e32 v50, vcc, s29, v42
	v_and_b32_e32 v27, 0x3f8, v27
	s_nop 0
	v_addc_co_u32_e32 v51, vcc, 0, v43, vcc
	v_add_co_u32_e32 v52, vcc, s30, v42
	s_addc_u32 s17, s23, 0
	s_nop 0
	v_addc_co_u32_e32 v53, vcc, 0, v43, vcc
	v_add_co_u32_e32 v54, vcc, s31, v42
	s_nop 1
	v_addc_co_u32_e32 v55, vcc, 0, v43, vcc
	v_add_co_u32_e32 v56, vcc, s25, v42
	s_nop 1
	v_addc_co_u32_e32 v57, vcc, 0, v43, vcc
	global_load_dword v40, v[42:43], off nt
	global_load_dword v41, v[44:45], off offset:3072 nt
	global_load_dword v37, v[46:47], off offset:2048 nt
	global_load_dword v38, v[48:49], off offset:1024 nt
	global_load_dword v35, v[50:51], off nt
	global_load_dword v36, v[52:53], off offset:3072 nt
	global_load_dword v34, v[54:55], off offset:2048 nt
	global_load_dword v39, v[56:57], off offset:1024 nt
	v_bfe_u32 v42, v33, 8, 1
	v_mul_lo_u32 v43, s3, v42
	v_mul_lo_u32 v42, s2, v42
	v_ashrrev_i32_e32 v44, 2, v33
	v_lshl_add_u64 v[42:43], v[42:43], 2, s[0:1]
	v_and_b32_e32 v44, 0xffffff80, v44
	v_mad_u64_u32 v[42:43], s[14:15], v27, s27, v[42:43]
	v_ashrrev_i32_e32 v45, 31, v44
	v_ashrrev_i32_e32 v33, 1, v33
	v_lshl_add_u64 v[42:43], v[44:45], 2, v[42:43]
	v_lshlrev_b32_e32 v44, 2, v33
	v_and_b32_e32 v44, 0x100, v44
	v_mov_b32_e32 v45, v153
	v_lshl_add_u64 v[42:43], v[42:43], 0, v[44:45]
	v_lshl_add_u64 v[50:51], v[42:43], 0, v[152:153]
	v_add_co_u32_e32 v52, vcc, s24, v50
	s_add_u32 s14, s20, 0xf000000
	s_nop 0
	v_addc_co_u32_e32 v53, vcc, 0, v51, vcc
	v_add_co_u32_e32 v54, vcc, s26, v50
	s_addc_u32 s15, s21, 0
	s_nop 0
	v_addc_co_u32_e32 v55, vcc, 0, v51, vcc
	v_add_co_u32_e32 v56, vcc, s28, v50
	s_nop 1
	v_addc_co_u32_e32 v57, vcc, 0, v51, vcc
	v_add_co_u32_e32 v58, vcc, s29, v50
	s_nop 1
	v_addc_co_u32_e32 v59, vcc, 0, v51, vcc
	v_add_co_u32_e32 v60, vcc, s30, v50
	s_nop 1
	v_addc_co_u32_e32 v61, vcc, 0, v51, vcc
	v_add_co_u32_e32 v62, vcc, 0x10000, v50
	s_nop 1
	v_addc_co_u32_e32 v63, vcc, 0, v51, vcc
	v_add_co_u32_e32 v64, vcc, 0x13000, v50
	s_nop 1
	v_addc_co_u32_e32 v65, vcc, 0, v51, vcc
	global_load_dword v48, v[50:51], off nt
	global_load_dword v49, v[52:53], off offset:3072 nt
	global_load_dword v45, v[54:55], off offset:2048 nt
	global_load_dword v46, v[56:57], off offset:1024 nt
	global_load_dword v43, v[58:59], off nt
	global_load_dword v44, v[60:61], off offset:3072 nt
	global_load_dword v42, v[62:63], off offset:2048 nt
	global_load_dword v47, v[64:65], off offset:1024 nt
	v_cmp_gt_i32_e32 vcc, s27, v185
	s_and_saveexec_b64 s[18:19], vcc
	s_cbranch_execnz .LBB0_1475
	s_or_b64 exec, exec, s[18:19]
	s_and_saveexec_b64 s[0:1], s[4:5]
	s_cbranch_execnz .LBB0_1476

; __device__ __forceinline__ void conv_addr(const ConvJob& j, int wi, int lane, const float*& src, int& stride, bf16_t*& dst, const float*& kg) {
;     ...
;     else { const int nb = wi / 352, k0 = (wi - nb * 352) * 8;
;         src = j.s0 + (size_t)k0 * D + nb * 64 + lane; stride = D; dst = j.dst + (size_t)(nb * 64 + lane) * FF + k0; kg = nullptr; }
; template <int NMAX>
; __device__ __forceinline__ void conv_block(const ConvJob& j, int total, int gw, int NW, int lane) {
;     if (j.kind == 0) return;
;     float v[NMAX][8]; bf16_t* d[NMAX]; const float* kg[NMAX];
; #pragma unroll
;     for (int q = 0; q < NMAX; ++q) { const int wi = gw + q * NW; const float* src; int st;
;         conv_addr(j, wi < total ? wi : gw, lane, src, st, d[q], kg[q]); conv_load(src, st, v[q]); }
.LBB0_1775:
	s_cmp_lt_i32 s74, 16
	s_cselect_b64 s[0:1], -1, 0
	s_cmp_gt_i32 s75, 15
	s_cselect_b64 s[2:3], -1, 0
	s_and_b64 s[0:1], s[0:1], s[2:3]
	s_andn2_b64 vcc, exec, s[0:1]
	s_cbranch_vccnz .LBB0_1890
	s_mov_b64 s[2:3], s[72:73]
	s_load_dwordx2 s[0:1], s[2:3], 0x30
	s_load_dwordx2 s[10:11], s[2:3], 0xa0
	s_add_i32 s2, 0, 0x2080c
	s_waitcnt vmcnt(0)
	v_mov_b32_e32 v8, v220
	v_mov_b32_e32 v0, s2
	ds_read_b32 v0, v0
	s_waitcnt lgkmcnt(0)
	v_ashrrev_i32_e32 v1, 6, v8
	s_lshl_b32 s2, s96, 3
	v_and_b32_e32 v146, 63, v8
	v_lshlrev_b32_e32 v128, 2, v146
	v_readfirstlane_b32 s33, v0
	v_lshl_add_u32 v147, v0, 3, v1
	v_and_b32_e32 v0, 1, v0
	v_cmp_eq_u32_e64 s[4:5], 0, v0
	v_add_u32_e32 v149, s2, v147
	s_and_b64 vcc, exec, s[4:5]
	v_add_u32_e32 v148, s2, v149
	s_cbranch_vccnz .LBB0_1782
	s_movk_i32 s16, 0x1600
	v_cmp_gt_i32_e64 s[6:7], s16, v149
	s_mov_b32 s17, 0x2e8ba2e9
	s_add_u32 s2, s0, 0x2100000
	v_cndmask_b32_e64 v0, v147, v149, s[6:7]
	v_mul_hi_i32 v1, v0, s17
	v_lshrrev_b32_e32 v2, 31, v1
	v_ashrrev_i32_e32 v1, 6, v1
	v_add_u32_e32 v6, v1, v2
	v_mul_i32_i24_e32 v1, 0xfffffea0, v6
	v_add_lshl_u32 v0, v1, v0, 3
	v_ashrrev_i32_e32 v1, 31, v0
	s_addc_u32 s3, s1, 0
	v_lshlrev_b64 v[2:3], 12, v[0:1]
	v_lshl_add_u64 v[4:5], s[2:3], 0, v[2:3]
	v_lshlrev_b32_e32 v2, 6, v6
	v_ashrrev_i32_e32 v3, 31, v2
	v_mov_b32_e32 v129, 0
	v_lshl_add_u64 v[4:5], v[2:3], 2, v[4:5]
	v_lshl_add_u64 v[24:25], v[4:5], 0, v[128:129]
	s_movk_i32 s18, 0x2000
	v_add_co_u32_e32 v26, vcc, s18, v24
	s_movk_i32 s19, 0x4000
	s_nop 0
	v_addc_co_u32_e32 v27, vcc, 0, v25, vcc
	v_add_co_u32_e32 v16, vcc, s19, v24
	s_movk_i32 s20, 0x6000
	s_nop 0
	v_addc_co_u32_e32 v17, vcc, 0, v25, vcc
	v_add_co_u32_e32 v18, vcc, s20, v24
	s_movk_i32 s8, 0x7000
	s_nop 0
	v_addc_co_u32_e32 v19, vcc, 0, v25, vcc
	v_add_co_u32_e32 v28, vcc, s8, v24
	v_cmp_gt_i32_e64 s[8:9], s16, v148
	s_nop 0
	v_addc_co_u32_e32 v29, vcc, 0, v25, vcc
	v_cndmask_b32_e64 v3, v147, v148, s[8:9]
	v_mul_hi_i32 v4, v3, s17
	v_lshrrev_b32_e32 v5, 31, v4
	v_ashrrev_i32_e32 v4, 6, v4
	v_add_u32_e32 v9, v4, v5
	v_mul_i32_i24_e32 v4, 0xfffffea0, v9
	v_add_lshl_u32 v4, v4, v3, 3
	v_ashrrev_i32_e32 v5, 31, v4
	v_lshlrev_b64 v[6:7], 12, v[4:5]
	v_lshl_add_u64 v[10:11], s[2:3], 0, v[6:7]
	v_lshlrev_b32_e32 v6, 6, v9
	v_ashrrev_i32_e32 v7, 31, v6
	v_lshl_add_u64 v[10:11], v[6:7], 2, v[10:11]
	v_lshl_add_u64 v[30:31], v[10:11], 0, v[128:129]
	v_add_co_u32_e32 v20, vcc, s18, v30
	s_movk_i32 s12, 0x5000
	s_nop 0
	v_addc_co_u32_e32 v21, vcc, 0, v31, vcc
	v_add_co_u32_e32 v22, vcc, s19, v30
	s_nop 1
	v_addc_co_u32_e32 v23, vcc, 0, v31, vcc
	v_add_co_u32_e32 v32, vcc, s12, v30
	global_load_dword v15, v[16:17], off offset:-4096 nt
	global_load_dword v12, v[16:17], off nt
	global_load_dword v13, v[18:19], off offset:-4096 nt
	global_load_dword v11, v[18:19], off nt
	global_load_dword v9, v[20:21], off offset:-4096 nt
	global_load_dword v3, v[20:21], off nt
	global_load_dword v10, v[22:23], off offset:-4096 nt
	global_load_dword v7, v[22:23], off nt
	v_addc_co_u32_e32 v33, vcc, 0, v31, vcc
	v_add_co_u32_e32 v34, vcc, 0x6000, v30
	s_add_u32 s12, s10, 0xfb00000
	s_nop 0
	v_addc_co_u32_e32 v35, vcc, 0, v31, vcc
	v_add_co_u32_e32 v36, vcc, 0x7000, v30
	s_addc_u32 s13, s11, 0
	s_nop 0
	v_addc_co_u32_e32 v37, vcc, 0, v31, vcc
	global_load_dword v21, v[24:25], off nt
	global_load_dword v22, v[26:27], off offset:-4096 nt
	global_load_dword v20, v[26:27], off nt
	global_load_dword v19, v[28:29], off nt
	global_load_dword v18, v[30:31], off nt
	global_load_dword v16, v[32:33], off nt
	global_load_dword v14, v[34:35], off nt
	global_load_dword v17, v[36:37], off nt
	v_cmp_gt_i32_e32 vcc, s16, v147
	s_and_saveexec_b64 s[14:15], vcc
	s_cbranch_execnz .LBB0_1812
	s_or_b64 exec, exec, s[14:15]
	s_and_saveexec_b64 s[2:3], s[6:7]
	s_cbranch_execnz .LBB0_1813

; __device__ __forceinline__ void conv_addr(const ConvJob& j, int wi, int lane, const float*& src, int& stride, bf16_t*& dst, const float*& kg) {
;     ...
;     else { const int nb = wi / 352, k0 = (wi - nb * 352) * 8;
;         src = j.s0 + (size_t)k0 * D + nb * 64 + lane; stride = D; dst = j.dst + (size_t)(nb * 64 + lane) * FF + k0; kg = nullptr; }
; template <int NMAX>
; __device__ __forceinline__ void conv_block(const ConvJob& j, int total, int gw, int NW, int lane) {
;     if (j.kind == 0) return;
;     float v[NMAX][8]; bf16_t* d[NMAX]; const float* kg[NMAX];
; #pragma unroll
;     for (int q = 0; q < NMAX; ++q) { const int wi = gw + q * NW; const float* src; int st;
;         conv_addr(j, wi < total ? wi : gw, lane, src, st, d[q], kg[q]); conv_load(src, st, v[q]); }
.LBB0_1796:
	s_movk_i32 s12, 0x1600
	v_cmp_gt_i32_e64 s[4:5], s12, v149
	s_mov_b32 s13, 0x2e8ba2e9
	s_add_u32 s0, s0, 0x2100000
	v_cndmask_b32_e64 v0, v147, v149, s[4:5]
	v_mul_hi_i32 v1, v0, s13
	v_lshrrev_b32_e32 v2, 31, v1
	v_ashrrev_i32_e32 v1, 6, v1
	v_add_u32_e32 v6, v1, v2
	v_mul_i32_i24_e32 v1, 0xfffffea0, v6
	v_add_lshl_u32 v0, v1, v0, 3
	v_ashrrev_i32_e32 v1, 31, v0
	s_addc_u32 s1, s1, 0
	v_lshlrev_b64 v[2:3], 12, v[0:1]
	v_lshl_add_u64 v[4:5], s[0:1], 0, v[2:3]
	v_lshlrev_b32_e32 v2, 6, v6
	v_ashrrev_i32_e32 v3, 31, v2
	v_cmp_gt_i32_e64 s[6:7], s12, v148
	v_mov_b32_e32 v129, 0
	v_lshl_add_u64 v[4:5], v[2:3], 2, v[4:5]
	v_cndmask_b32_e64 v3, v147, v148, s[6:7]
	v_lshl_add_u64 v[22:23], v[4:5], 0, v[128:129]
	v_mul_hi_i32 v4, v3, s13
	v_lshrrev_b32_e32 v5, 31, v4
	v_ashrrev_i32_e32 v4, 6, v4
	s_movk_i32 s14, 0x2000
	v_add_u32_e32 v10, v4, v5
	v_add_co_u32_e32 v24, vcc, s14, v22
	v_mul_i32_i24_e32 v4, 0xfffffea0, v10
	s_nop 0
	v_addc_co_u32_e32 v25, vcc, 0, v23, vcc
	s_movk_i32 s15, 0x4000
	v_add_lshl_u32 v4, v4, v3, 3
	v_add_co_u32_e32 v16, vcc, s15, v22
	v_ashrrev_i32_e32 v5, 31, v4
	s_nop 0
	v_addc_co_u32_e32 v17, vcc, 0, v23, vcc
	s_movk_i32 s16, 0x6000
	v_lshlrev_b64 v[6:7], 12, v[4:5]
	v_add_co_u32_e32 v18, vcc, s16, v22
	v_lshl_add_u64 v[8:9], s[0:1], 0, v[6:7]
	v_lshlrev_b32_e32 v6, 6, v10
	v_addc_co_u32_e32 v19, vcc, 0, v23, vcc
	s_movk_i32 s3, 0x7000
	v_ashrrev_i32_e32 v7, 31, v6
	v_add_co_u32_e32 v26, vcc, s3, v22
	v_lshl_add_u64 v[8:9], v[6:7], 2, v[8:9]
	s_nop 0
	v_addc_co_u32_e32 v27, vcc, 0, v23, vcc
	v_lshl_add_u64 v[28:29], v[8:9], 0, v[128:129]
	v_add_co_u32_e32 v20, vcc, s14, v28
	s_movk_i32 s2, 0x5000
	s_nop 0
	v_addc_co_u32_e32 v21, vcc, 0, v29, vcc
	v_add_co_u32_e32 v30, vcc, s15, v28
	s_nop 1
	v_addc_co_u32_e32 v31, vcc, 0, v29, vcc
	global_load_dword v14, v[16:17], off offset:-4096 nt
	global_load_dword v11, v[16:17], off nt
	global_load_dword v12, v[18:19], off offset:-4096 nt
	global_load_dword v10, v[18:19], off nt
	global_load_dword v8, v[20:21], off offset:-4096 nt
	global_load_dword v3, v[20:21], off nt
	global_load_dword v9, v[30:31], off offset:-4096 nt
	global_load_dword v7, v[30:31], off nt
	v_add_co_u32_e32 v30, vcc, s2, v28
	s_add_u32 s2, s10, 0xfb00000
	s_nop 0
	v_addc_co_u32_e32 v31, vcc, 0, v29, vcc
	v_add_co_u32_e32 v32, vcc, 0x6000, v28
	s_addc_u32 s3, s11, 0
	s_nop 0
	v_addc_co_u32_e32 v33, vcc, 0, v29, vcc
	v_add_co_u32_e32 v34, vcc, 0x7000, v28
	s_nop 1
	v_addc_co_u32_e32 v35, vcc, 0, v29, vcc
	global_load_dword v20, v[22:23], off nt
	global_load_dword v21, v[24:25], off offset:-4096 nt
	global_load_dword v19, v[24:25], off nt
	global_load_dword v18, v[26:27], off nt
	global_load_dword v17, v[28:29], off nt
	global_load_dword v15, v[30:31], off nt
	global_load_dword v13, v[32:33], off nt
	global_load_dword v16, v[34:35], off nt
	v_cmp_gt_i32_e32 vcc, s12, v147
	s_and_saveexec_b64 s[8:9], vcc
	s_cbranch_execnz .LBB0_1814
	s_or_b64 exec, exec, s[8:9]
	s_and_saveexec_b64 s[0:1], s[4:5]
	s_cbranch_execnz .LBB0_1815
